# attention: row-sum accumulation moved from QK region to PV region; QK accumulators initialised with -m tuple so no max subtraction in common path
# speedup vs baseline: 1.0101x; 1.0101x over previous
;     __host__ __device__ bool next(int i, Unit& u) const {
;         const long L = (long)i * G + c; if (L >= nwg) return false;
;         int wgid = (int)L; { const int q = nwg / NXCD, r = nwg % NXCD, xcd = wgid % NXCD, off = wgid / NXCD; wgid = (xcd < r ? xcd * (q + 1) : r * (q + 1) + (xcd - r) * q) + off; }
;         const int nig = WGM * nN, gid = wgid / nig, fm = gid * WGM, gsz = (nM - fm) < WGM ? (nM - fm) : WGM;
;         u.pm = fm + ((wgid % nig) % gsz); u.pn = (wgid % nig) / gsz; return true;
;     }
; template <class Epi, class Sched, bool ALIGN_EPI = false, bool SP2 = false>
; __device__ __forceinline__ void gemm_phase(PG8_LAS unsigned char* lds, const Gemm g, const Sched& S, const Epi& E) {
;     ...
;         const bool has_next = S.next(ui + 1, nxt);
.LBB0_135:
	s_add_i32 s75, s75, 1
	s_mul_i32 s38, s75, s49
	s_mul_hi_u32 s39, s75, s98
	s_add_i32 s39, s39, s38
	s_mul_i32 s38, s75, s98
	s_add_u32 s84, s38, s2
	s_addc_u32 s85, s39, s48
	v_mov_b64_e32 v[0:1], 0x600
	v_mov_b64_e32 v[164:165], 0x5ff
	v_cmp_gt_i64_e32 vcc, s[84:85], v[164:165]
	v_cmp_lt_i64_e64 s[38:39], s[84:85], v[0:1]
	s_cbranch_vccnz .LBB0_137
	s_ashr_i32 s44, s84, 31
	s_lshr_b32 s44, s44, 29
	s_add_i32 s44, s84, s44
	s_ashr_i32 s45, s44, 3
	s_and_b32 s44, s44, -8
	s_sub_i32 s44, s84, s44
	s_cmp_lt_i32 s44, 0
	s_cselect_b32 s46, s16, 0xc0
	s_mul_i32 s44, s44, s46
	s_add_i32 s44, s44, s45
	s_mul_hi_i32 s45, s44, 0x2aaaaaab
	s_lshr_b32 s46, s45, 31
	s_ashr_i32 s45, s45, 5
	s_add_i32 s45, s45, s46
	s_lshl_b32 s46, s45, 3
	s_sub_i32 s47, 64, s46
	s_min_i32 s47, s47, 8
	s_abs_i32 s78, s47
	v_cvt_f32_u32_e32 v0, s78
	s_sub_i32 s81, 0, s78
	s_mulk_i32 s45, 0xc0
	s_sub_i32 s45, s44, s45
	v_rcp_iflag_f32_e32 v0, v0
	s_abs_i32 s44, s45
	s_xor_b32 s79, s45, s47
	s_ashr_i32 s79, s79, 31
	v_mul_f32_e32 v0, 0x4f7ffffe, v0
	v_cvt_u32_f32_e32 v0, v0
	s_nop 0
	v_readfirstlane_b32 s82, v0
	s_mul_i32 s81, s81, s82
	s_mul_hi_u32 s81, s82, s81
	s_add_i32 s82, s82, s81
	s_mul_hi_u32 s81, s44, s82
	s_mul_i32 s82, s81, s78
	s_sub_i32 s44, s44, s82
	s_add_i32 s83, s81, 1
	s_sub_i32 s82, s44, s78
	s_cmp_ge_u32 s44, s78
	s_cselect_b32 s81, s83, s81
	s_cselect_b32 s44, s82, s44
	s_add_i32 s82, s81, 1
	s_cmp_ge_u32 s44, s78
	s_cselect_b32 s44, s82, s81
	s_xor_b32 s44, s44, s79
	s_sub_i32 s44, s44, s79
	s_mul_i32 s47, s44, s47
	s_sub_i32 s45, s45, s47
	s_add_i32 s82, s46, s45

; __device__ __forceinline__ int v_rd_base(int lane) { return ((lane & 3) << 3) | (((lane >> 2) & 3) << 6) | (((lane >> 4) & 1) << 5) | (((lane >> 5) & 1) << 8); }
; #define WAIT_BAR(N) asm volatile("s_waitcnt vmcnt(" #N ") lgkmcnt(0)\n\ts_barrier" ::: "memory")
; __device__ __forceinline__ void attn_unit(const bf16* __restrict__ proj, bf16* __restrict__ cat, int b, int h, int qb, float lam, float oscale, const float* __restrict__ subln, const float* __restrict__ cw, char* lds) {
;   int tid_ = threadIdx.x; asm volatile("" : "+v"(tid_));
;   const int tid = tid_, wid = __builtin_amdgcn_readfirstlane(tid >> 6), lane = tid & 63, r32 = lane & 31, hi = lane >> 5, rg = wid & 3, mp = wid >> 2;
;   char* K_lds = lds; char* V_lds = lds + 3 * SHM_K;
;   float* ws = (float*)(lds + OFF_WS) + wid * 64; float* li_l = ws; float* al_l = ws + 32;
;   const long rowbase = (long)b * SEQ;
;   const bf16* Kh = proj + rowbase * LDP + 1024 + h * 128; const bf16* Vh = proj + rowbase * LDP + 2048 + h * 128;
;   float m_reg = -1e30f, l_reg = 0; f32x16 o[4] = {}; bf16x8 qr[4];
;   const bf16* Qw = proj + (rowbase + qb * QROWS + rg * 32 + r32) * LDP + (2 * h + mp) * 64 + hi * 8;
; #pragma unroll
;   for (int d0 = 0; d0 < 4; ++d0) qr[d0] = *reinterpret_cast<const bf16x8*>(Qw + d0 * 16);
;   const int cbase = mp * 128;
;   unsigned kofs[2], vofs[2];
; #pragma unroll
;   for (int i = 0; i < 2; ++i) { const int q = wid + 8 * i, p = 64 * q + lane;
;     const int krow = p >> 4, kc8 = (p & 15) ^ (krow & 15); kofs[i] = (unsigned)(krow * LDP + kc8 * 8) * 2u;
;     const int kk = (p >> 7) * 8 + ((p & 31) >> 2), c = ((p >> 5) & 3) * 32 + (p & 3) * 8, k = (kk & ~0xC) | ((kk & 4) << 1) | ((kk & 8) >> 1); vofs[i] = (unsigned)(k * LDP + c) * 2u; }
;   const unsigned lds0 = (unsigned)(uintptr_t)lds, kdst = lds0 + wid * 1024, vdst = lds0 + 3 * SHM_K + wid * 1024;
;     ...
;   const int vb0 = (int)(lds0 + 3 * SHM_K) + v_rd_base(lane);
;     ...
;   f32x16 pA0, pA1, pB0, pB1; float mnA, mnB, alA, alB; bf16x8 pa0, pa1, pa2, pa3; constexpr int NT = SEQ / KVBLK;
;   asm volatile("s_waitcnt vmcnt(0)" ::: "memory");
;   DMA_K(0, 0); DMA_V(0, 0); DMA_K(1, 1);
;   WAIT_BAR(2);
;   qkt(pA0, pA1, K_lds, qr, r32, hi, cbase); partialSM(pA0, pA1, m_reg, mnA, alA);
.Latt_noprio:
	s_add_i32 s70, s70, 0x18000
	s_lshl_b64 s[44:45], s[46:47], 12
	s_mul_i32 s21, s46, 0x3000000
	s_mul_hi_i32 s20, s46, 0x3000000
	s_add_u32 s46, s66, s21
	s_addc_u32 s47, s67, s20
	s_lshl_b32 s38, s38, 7
	s_and_b32 s38, s38, 0xf80
	s_or_b32 s38, s44, s38
	s_lshl_b32 s39, s25, 5
	v_and_b32_e32 v174, 31, v8
	s_or_b32 s44, s38, s39
	v_or_b32_e32 v2, s44, v174
	v_mov_b64_e32 v[0:1], s[66:67]
	s_lshl_b32 s28, s73, 7
	v_mad_u64_u32 v[0:1], s[38:39], v2, s1, v[0:1]
	s_and_b32 s28, s28, 0x380
	s_lshl_b32 s38, s24, 6
	s_add_i32 s38, s38, s28
	v_bfe_u32 v179, v8, 5, 1
	v_mad_i32_i24 v1, s45, v200, v1
	s_ashr_i32 s39, s38, 31
	v_lshl_add_u64 v[0:1], s[38:39], 1, v[0:1]
	v_lshlrev_b32_e32 v162, 4, v179
	v_lshl_add_u64 v[0:1], v[0:1], 0, v[162:163]
	global_load_dwordx4 v[140:143], v[0:1], off
	global_load_dwordx4 v[136:139], v[0:1], off offset:32
	global_load_dwordx4 v[132:135], v[0:1], off offset:64
	global_load_dwordx4 v[128:131], v[0:1], off offset:96
	s_lshl_b32 s38, s28, 1
	s_add_u32 s75, s46, s38
	v_mov_b32_e32 v2, s31
	s_movk_i32 s38, 0xffc0
	s_addc_u32 s77, s47, 0
	v_bfi_b32 v2, s38, v2, v8
	s_add_u32 s46, s75, 0x1000
	v_ashrrev_i32_e32 v2, 4, v2
	s_addc_u32 s47, s77, 0
	v_xor_b32_e32 v3, v2, v8
	s_ashr_i32 s38, s71, 4
	v_mul_lo_u32 v2, v2, s33
	v_lshlrev_b32_e32 v3, 3, v3
	s_and_b32 s39, s38, 0x1ffff0
	s_lshr_b32 s38, s38, 1
	v_and_b32_e32 v177, 63, v8
	v_bfe_u32 v0, v8, 2, 3
	v_lshrrev_b32_e32 v180, 1, v8
	v_and_or_b32 v2, v3, s0, v2
	s_and_b32 s38, s38, 4
	v_lshlrev_b32_e32 v184, 1, v2
	v_bitop3_b32 v2, s71, v201, v177 bitop3:0xc8
	s_lshr_b32 s38, s71, 7
	s_lshl_b32 s38, s38, 3
	s_addk_i32 s71, 0x200
	v_lshlrev_b32_e32 v178, 3, v8
	v_or_b32_e32 v3, s38, v0
	s_ashr_i32 s38, s71, 4
	v_and_b32_e32 v1, 24, v178
	v_mul_u32_u24_e32 v3, 0x1800, v3
	s_and_b32 s39, s38, 0x1ffff0
	s_lshr_b32 s38, s38, 1
	v_or3_b32 v2, v3, v2, v1
	s_and_b32 s38, s38, 4
	v_lshlrev_b32_e32 v185, 1, v2
	v_or_b32_e32 v2, s71, v177
	s_lshr_b32 s38, s71, 7
	s_lshl_b32 s38, s38, 3
	v_ashrrev_i32_e32 v2, 4, v2
	s_add_u32 s78, s75, 0x800
	v_xor_b32_e32 v3, v2, v8
	s_addc_u32 s79, s77, 0
	s_lshl_b32 s39, s24, 7
	s_lshl_b32 s72, s29, 10
	v_mul_lo_u32 v2, v2, s33
	v_lshlrev_b32_e32 v3, 3, v3
	s_cmp_lg_u32 0, -1
	v_and_or_b32 v2, v3, s0, v2
	v_or_b32_e32 v0, s38, v0
	s_cselect_b32 s38, 0, 0
	s_waitcnt vmcnt(0)
	v_lshlrev_b32_e32 v186, 1, v2
	v_bitop3_b32 v2, s71, v201, v177 bitop3:0xc8
	s_add_i32 s71, s72, s38
	s_mov_b32 s74, m0
	s_mov_b32 m0, s71
	s_nop 0
	global_load_lds_dwordx4 v184, s[78:79]
	s_mov_b32 m0, s74
	s_add_i32 s38, s38, 0xc000
	s_add_i32 s74, s71, 0x2000
	s_mov_b32 s76, m0
	s_mov_b32 m0, s74
	s_nop 0
	global_load_lds_dwordx4 v186, s[78:79]
	s_mov_b32 m0, s76
	v_mul_u32_u24_e32 v0, 0x1800, v0
	s_add_i32 s72, s72, s38
	s_mov_b32 s74, m0
	s_mov_b32 m0, s72
	s_nop 0
	global_load_lds_dwordx4 v185, s[46:47]
	s_mov_b32 m0, s74
	v_or3_b32 v0, v0, v2, v1
	s_add_i32 s74, s71, 0xe000
	v_lshlrev_b32_e32 v187, 1, v0
	v_lshlrev_b32_e32 v9, 4, v8
	s_mov_b32 s76, m0
	s_mov_b32 m0, s74
	s_nop 0
	global_load_lds_dwordx4 v187, s[46:47]
	s_mov_b32 m0, s76
	s_add_u32 s46, s75, 0xc0800
	s_addc_u32 s47, s77, 0
	s_add_i32 s74, s71, 0x4000
	s_mov_b32 s76, m0
	s_mov_b32 m0, s74
	s_nop 0
	global_load_lds_dwordx4 v184, s[46:47]
	s_mov_b32 m0, s76
	v_and_b32_e32 v10, 0xf0, v9
	s_add_i32 s74, s71, 0x6000
	s_mov_b32 s76, m0
	s_mov_b32 m0, s74
	s_nop 0
	global_load_lds_dwordx4 v186, s[46:47]
	s_mov_b32 m0, s76
	v_lshl_add_u32 v189, v174, 8, 0
	v_bitop3_b32 v210, s39, v10, v162 bitop3:0x36
	s_waitcnt vmcnt(2) lgkmcnt(0)
	s_barrier
	v_add_u32_e32 v188, v189, v210
	ds_read_b128 v[0:3], v188
	ds_read_b128 v[4:7], v188 offset:8192
	s_waitcnt vmcnt(3) lgkmcnt(1)
	v_mfma_f32_32x32x16_bf16 v[32:47], v[0:3], v[140:143], 0
	v_or_b32_e32 v11, s39, v162
	v_bitop3_b32 v212, v11, v10, 32 bitop3:0x36
	v_add_u32_e32 v211, v189, v212
	v_bitop3_b32 v214, v11, v10, 64 bitop3:0x36
	v_add_u32_e32 v213, v189, v214
	s_movk_i32 s39, 0x60
	v_lshlrev_b32_e32 v181, 3, v177
	s_waitcnt lgkmcnt(0)
	v_mfma_f32_32x32x16_bf16 v[16:31], v[4:7], v[140:143], 0
	ds_read_b128 v[0:3], v211
	ds_read_b128 v[4:7], v211 offset:8192
	v_bitop3_b32 v216, v11, v10, s39 bitop3:0x36
	v_add_u32_e32 v215, v189, v216
	ds_read_b128 v[48:51], v215 offset:8192
	v_readlane_b32 s80, v255, 8
	s_mov_b32 s8, s80
	v_readlane_b32 s81, v255, 9
	s_waitcnt vmcnt(2) lgkmcnt(2)
	v_mfma_f32_32x32x16_bf16 v[32:47], v[0:3], v[136:139], v[32:47]
	ds_read_b128 v[0:3], v213
	v_readlane_b32 s82, v255, 10
	v_readlane_b32 s83, v255, 11
	v_readlane_b32 s84, v255, 12
	v_readlane_b32 s85, v255, 13
	v_readlane_b32 s86, v255, 14
	v_readlane_b32 s87, v255, 15
	s_waitcnt lgkmcnt(2)
	v_mfma_f32_32x32x16_bf16 v[16:31], v[4:7], v[136:139], v[16:31]
	v_and_b32_e32 v4, 0xc0, v9
	v_and_or_b32 v9, v181, 24, v4
	v_lshlrev_b32_e32 v4, 1, v8
	v_and_b32_e32 v8, 32, v4
	ds_read_b128 v[4:7], v213 offset:8192
	v_readlane_b32 s88, v255, 16
	v_readlane_b32 s89, v255, 17
	s_waitcnt vmcnt(1) lgkmcnt(1)
	v_mfma_f32_32x32x16_bf16 v[32:47], v[0:3], v[132:135], v[32:47]
	ds_read_b128 v[0:3], v215
	v_readlane_b32 s90, v255, 18
	v_readlane_b32 s91, v255, 19
	v_readlane_b32 s92, v255, 20
	v_readlane_b32 s93, v255, 21
	v_readlane_b32 s94, v255, 22
	v_readlane_b32 s95, v255, 23
	s_waitcnt lgkmcnt(1)
	v_mfma_f32_32x32x16_bf16 v[16:31], v[4:7], v[132:135], v[16:31]
	v_writelane_b32 v255, s8, 8
	v_and_b32_e32 v12, 0x100, v181
	v_or3_b32 v183, v9, v8, v12
	v_writelane_b32 v255, s9, 9
	v_writelane_b32 v255, s10, 10
	v_writelane_b32 v255, s11, 11
	v_writelane_b32 v255, s12, 12
	s_waitcnt vmcnt(0) lgkmcnt(0)
; #define WAIT_BAR(N) asm volatile("s_waitcnt vmcnt(" #N ") lgkmcnt(0)\n\ts_barrier" ::: "memory")
; #define DMA_K(t, slot) do { const bf16* kb_ = Kh + (long)(t) * KVBLK * LDP; glds16(kb_, kofs[0], kdst + (slot) * SHM_K); glds16(kb_, kofs[1], kdst + (slot) * SHM_K + 8192); } while (0)
; #define DMA_V(t, slot) do { const bf16* vb_ = Vh + (long)(t) * KVBLK * LDP; glds16(vb_, vofs[0], vdst + (slot) * SHM_V); glds16(vb_, vofs[1], vdst + (slot) * SHM_V + 8192); } while (0)
; __device__ __forceinline__ void partialSM(f32x16& p0, f32x16& p1, float& m_reg, float& mn, float& alpha) {
;   float pmax = p0[0];
; #pragma unroll
;   for (int r = 1; r < 16; ++r) pmax = fmaxf(pmax, p0[r]);
; #pragma unroll
;   for (int r = 0; r < 16; ++r) pmax = fmaxf(pmax, p1[r]);
;   { auto rr = __builtin_amdgcn_permlane32_swap(__float_as_uint(pmax), __float_as_uint(pmax), false, false);
;     pmax = fmaxf(__uint_as_float(rr[0]), __uint_as_float(rr[1])); }
;   if (__builtin_expect(__all(pmax - m_reg <= THR), 1)) { mn = m_reg; alpha = 1.f; }
;   else { mn = fmaxf(m_reg, pmax); alpha = __builtin_amdgcn_exp2f(m_reg - mn); m_reg = mn; }
; #pragma unroll
;   for (int r = 0; r < 16; ++r) p0[r] = p0[r] - mn;
; #pragma unroll
;   for (int r = 0; r < 16; ++r) p1[r] = p1[r] - mn;
; #pragma unroll
;   for (int r = 0; r < 16; ++r) p0[r] = __builtin_amdgcn_exp2f(p0[r]);
; }
; __device__ __forceinline__ void attn_unit(const bf16* __restrict__ proj, bf16* __restrict__ cat, int b, int h, int qb, float lam, float oscale, const float* __restrict__ subln, const float* __restrict__ cw, char* lds) {
;     ...
;   qkt(pA0, pA1, K_lds, qr, r32, hi, cbase); partialSM(pA0, pA1, m_reg, mnA, alA);
; #pragma unroll
;   for (int r = 0; r < 16; ++r) pA1[r] = __builtin_amdgcn_exp2f(pA1[r]);
;   DMA_V(1, 1); DMA_K(2, 2);
;   WAIT_BAR(4);
	v_mfma_f32_32x32x16_bf16 v[32:47], v[0:3], v[128:131], v[32:47]
	v_writelane_b32 v255, s13, 13
	v_writelane_b32 v255, s14, 14
	v_writelane_b32 v255, s15, 15
	v_add_u32_e32 v217, s38, v183
	v_writelane_b32 v255, s16, 16
	v_writelane_b32 v255, s17, 17
	v_writelane_b32 v255, s18, 18
	v_mfma_f32_32x32x16_bf16 v[16:31], v[48:51], v[128:131], v[16:31]
	s_nop 3
	v_max_f32_e32 v48, v33, v33
	v_max_f32_e32 v49, v32, v32
	v_max_f32_e32 v48, v49, v48
	v_max3_f32 v48, v48, v34, v35
	v_max3_f32 v48, v48, v36, v37
	v_max3_f32 v48, v48, v38, v39
	v_max3_f32 v48, v48, v40, v41
	v_max3_f32 v48, v48, v42, v43
	v_max3_f32 v48, v48, v44, v45
	v_max3_f32 v48, v48, v46, v47
	v_max3_f32 v48, v48, v16, v17
	v_max3_f32 v48, v48, v18, v19
	v_max3_f32 v48, v48, v20, v21
	v_max3_f32 v48, v48, v22, v23
	v_max3_f32 v48, v48, v24, v25
	v_max3_f32 v48, v48, v26, v27
	v_max3_f32 v48, v48, v28, v29
	v_max3_f32 v48, v48, v30, v31
	v_mov_b32_e32 v49, v48
	s_nop 1
	v_permlane32_swap_b32_e32 v48, v49
	v_max_f32_e32 v49, v49, v49
	v_max_f32_e32 v48, v48, v48
	v_max_f32_e32 v48, v48, v49
	v_add_f32_e32 v49, 0x7149f2ca, v48
	v_cmp_ge_f32_e32 vcc, s6, v49
	s_cmp_eq_u64 vcc, exec
	s_cselect_b64 vcc, -1, 0
	s_add_u32 s38, s75, 0xc1000
	s_addc_u32 s39, s77, 0
	s_add_i32 s46, s71, 0x10000
	s_mov_b32 s47, m0
	s_mov_b32 m0, s46
	s_nop 0
	global_load_lds_dwordx4 v185, s[38:39]
	s_mov_b32 m0, s47
	s_add_i32 s46, s71, 0x12000
	s_mov_b32 s47, m0
	s_mov_b32 m0, s46
	s_nop 0
	global_load_lds_dwordx4 v187, s[38:39]
	s_mov_b32 m0, s47
	s_add_u32 s38, s75, 0x180800
	v_writelane_b32 v255, s19, 19
	v_max_f32_e32 v48, 0xf149f2ca, v48
	s_addc_u32 s39, s77, 0
	s_add_i32 s46, s71, 0x8000
	v_writelane_b32 v255, s20, 20
	v_cndmask_b32_e32 v218, v48, v202, vcc
	s_mov_b32 s47, m0
	s_mov_b32 m0, s46
	s_nop 0
	global_load_lds_dwordx4 v184, s[38:39]
	s_mov_b32 m0, s47
	s_add_i32 s46, s71, 0xa000
	v_writelane_b32 v255, s21, 21
	v_sub_f32_e32 v49, 0xf149f2ca, v48
	v_sub_f32_e32 v16, v16, v218
	s_mov_b32 s47, m0
	s_mov_b32 m0, s46
	s_nop 0
	global_load_lds_dwordx4 v186, s[38:39]
	s_mov_b32 m0, s47
	s_and_b32 s46, s73, 7
	v_writelane_b32 v255, s22, 22
	v_exp_f32_e32 v64, v16
	v_exp_f32_e32 v16, v49
	s_lshl_b32 s46, s46, 8
	s_mov_b32 s81, s80
	v_writelane_b32 v255, s23, 23
	v_sub_f32_e32 v32, v32, v218
	v_sub_f32_e32 v33, v33, v218
	v_sub_f32_e32 v34, v34, v218
	v_sub_f32_e32 v35, v35, v218
	v_sub_f32_e32 v36, v36, v218
	v_sub_f32_e32 v37, v37, v218
	v_sub_f32_e32 v38, v38, v218
	v_sub_f32_e32 v39, v39, v218
	v_sub_f32_e32 v40, v40, v218
	v_sub_f32_e32 v41, v41, v218
	v_sub_f32_e32 v42, v42, v218
	v_sub_f32_e32 v43, v43, v218
	v_sub_f32_e32 v44, v44, v218
	v_sub_f32_e32 v45, v45, v218
	v_sub_f32_e32 v46, v46, v218
	v_sub_f32_e32 v47, v47, v218
	v_sub_f32_e32 v17, v17, v218
	v_sub_f32_e32 v18, v18, v218
	v_sub_f32_e32 v19, v19, v218
	v_sub_f32_e32 v20, v20, v218
	v_sub_f32_e32 v21, v21, v218
	v_sub_f32_e32 v22, v22, v218
	v_sub_f32_e32 v23, v23, v218
	v_sub_f32_e32 v24, v24, v218
	v_sub_f32_e32 v25, v25, v218
	v_sub_f32_e32 v26, v26, v218
	v_sub_f32_e32 v27, v27, v218
	v_sub_f32_e32 v28, v28, v218
	v_sub_f32_e32 v29, v29, v218
	v_sub_f32_e32 v30, v30, v218
	v_sub_f32_e32 v31, v31, v218
	s_or_b32 s21, s21, s46
	s_mov_b32 s82, s80
	s_mov_b32 s83, s80
	s_mov_b32 s84, s80
	s_mov_b32 s85, s80
	s_mov_b32 s86, s80
	s_mov_b32 s87, s80
	s_mov_b32 s88, s80
	s_mov_b32 s89, s80
	s_mov_b32 s90, s80
	s_mov_b32 s91, s80
	s_mov_b32 s92, s80
	s_mov_b32 s93, s80
	s_mov_b32 s94, s80
	s_mov_b32 s95, s80
	v_mov_b64_e32 v[0:1], s[80:81]
	v_exp_f32_e32 v80, v32
	v_exp_f32_e32 v81, v33
	v_exp_f32_e32 v82, v34
	v_exp_f32_e32 v83, v35
	v_exp_f32_e32 v84, v36
	v_exp_f32_e32 v85, v37
	v_exp_f32_e32 v86, v38
	v_exp_f32_e32 v87, v39
	v_exp_f32_e32 v88, v40
	v_exp_f32_e32 v89, v41
	v_exp_f32_e32 v90, v42
	v_exp_f32_e32 v91, v43
	v_exp_f32_e32 v92, v44
	v_exp_f32_e32 v93, v45
	v_exp_f32_e32 v94, v46
	v_exp_f32_e32 v95, v47
	v_exp_f32_e32 v65, v17
	v_exp_f32_e32 v66, v18
	v_exp_f32_e32 v67, v19
	v_exp_f32_e32 v68, v20
	v_exp_f32_e32 v69, v21
	v_exp_f32_e32 v70, v22
	v_exp_f32_e32 v71, v23
	v_exp_f32_e32 v72, v24
	v_exp_f32_e32 v73, v25
	v_exp_f32_e32 v74, v26
	v_exp_f32_e32 v75, v27
	v_exp_f32_e32 v76, v28
	v_exp_f32_e32 v77, v29
	v_exp_f32_e32 v78, v30
	v_exp_f32_e32 v79, v31
	s_add_u32 s73, s3, s21
	v_mov_b64_e32 v[14:15], s[94:95]
	s_waitcnt vmcnt(4) lgkmcnt(0)
	s_barrier
; __device__ __forceinline__ int v_rd_base(int lane) { return ((lane & 3) << 3) | (((lane >> 2) & 3) << 6) | (((lane >> 4) & 1) << 5) | (((lane >> 5) & 1) << 8); }
; #define WAIT_BAR(N) asm volatile("s_waitcnt vmcnt(" #N ") lgkmcnt(0)\n\ts_barrier" ::: "memory")
; #define DMA_K(t, slot) do { const bf16* kb_ = Kh + (long)(t) * KVBLK * LDP; glds16(kb_, kofs[0], kdst + (slot) * SHM_K); glds16(kb_, kofs[1], kdst + (slot) * SHM_K + 8192); } while (0)
; #define DMA_V(t, slot) do { const bf16* vb_ = Vh + (long)(t) * KVBLK * LDP; glds16(vb_, vofs[0], vdst + (slot) * SHM_V); glds16(vb_, vofs[1], vdst + (slot) * SHM_V + 8192); } while (0)
; __device__ __forceinline__ void attn_unit(const bf16* __restrict__ proj, bf16* __restrict__ cat, int b, int h, int qb, float lam, float oscale, const float* __restrict__ subln, const float* __restrict__ cw, char* lds) {
;     ...
;   float m_reg = -1e30f, l_reg = 0; f32x16 o[4] = {}; bf16x8 qr[4];
;   const bf16* Qw = proj + (rowbase + qb * QROWS + rg * 32 + r32) * LDP + (2 * h + mp) * 64 + hi * 8;
; #pragma unroll
;   for (int d0 = 0; d0 < 4; ++d0) qr[d0] = *reinterpret_cast<const bf16x8*>(Qw + d0 * 16);
;   const int cbase = mp * 128;
;   unsigned kofs[2], vofs[2];
; #pragma unroll
;   for (int i = 0; i < 2; ++i) { const int q = wid + 8 * i, p = 64 * q + lane;
;     const int krow = p >> 4, kc8 = (p & 15) ^ (krow & 15); kofs[i] = (unsigned)(krow * LDP + kc8 * 8) * 2u;
;     const int kk = (p >> 7) * 8 + ((p & 31) >> 2), c = ((p >> 5) & 3) * 32 + (p & 3) * 8, k = (kk & ~0xC) | ((kk & 4) << 1) | ((kk & 8) >> 1); vofs[i] = (unsigned)(k * LDP + c) * 2u; }
;   const unsigned lds0 = (unsigned)(uintptr_t)lds, kdst = lds0 + wid * 1024, vdst = lds0 + 3 * SHM_K + wid * 1024;
;     ...
;   const int vb0 = (int)(lds0 + 3 * SHM_K) + v_rd_base(lane);
;     ...
;   f32x16 pA0, pA1, pB0, pB1; float mnA, mnB, alA, alB; bf16x8 pa0, pa1, pa2, pa3; constexpr int NT = SEQ / KVBLK;
;   asm volatile("s_waitcnt vmcnt(0)" ::: "memory");
;   DMA_K(0, 0); DMA_V(0, 0); DMA_K(1, 1);
;   WAIT_BAR(2);
;   qkt(pA0, pA1, K_lds, qr, r32, hi, cbase); partialSM(pA0, pA1, m_reg, mnA, alA);
; #pragma unroll
;   for (int r = 0; r < 16; ++r) pA1[r] = __builtin_amdgcn_exp2f(pA1[r]);
;   DMA_V(1, 1); DMA_K(2, 2);
;   WAIT_BAR(4);
;   int sj = 1;
	s_addc_u32 s74, s62, s20
	v_mov_b64_e32 v[2:3], s[82:83]
	v_mov_b64_e32 v[4:5], s[84:85]
	v_mov_b64_e32 v[6:7], s[86:87]
	v_mov_b64_e32 v[8:9], s[88:89]
	v_mov_b64_e32 v[10:11], s[90:91]
	v_mov_b64_e32 v[12:13], s[92:93]
	v_cndmask_b32_e64 v220, v16, 1.0, vcc
	s_add_u32 s82, s75, 0x240800
	v_mov_b64_e32 v[62:63], v[14:15]
	v_mov_b64_e32 v[46:47], v[14:15]
	v_mov_b64_e32 v[30:31], v[14:15]
	s_mov_b32 s76, 1
	v_cmp_gt_u32_e64 s[38:39], 32, v177
	v_lshl_add_u32 v182, v174, 2, s70
	s_addc_u32 s83, s77, 0
	v_mov_b32_e32 v219, 0
	v_mov_b64_e32 v[60:61], v[12:13]
	v_mov_b64_e32 v[58:59], v[10:11]
	v_mov_b64_e32 v[56:57], v[8:9]
	v_mov_b64_e32 v[54:55], v[6:7]
	v_mov_b64_e32 v[52:53], v[4:5]
	v_mov_b64_e32 v[50:51], v[2:3]
	v_mov_b64_e32 v[48:49], v[0:1]
	v_mov_b64_e32 v[44:45], v[12:13]
	v_mov_b64_e32 v[42:43], v[10:11]
	v_mov_b64_e32 v[40:41], v[8:9]
	v_mov_b64_e32 v[38:39], v[6:7]
	v_mov_b64_e32 v[36:37], v[4:5]
	v_mov_b64_e32 v[34:35], v[2:3]
	v_mov_b64_e32 v[32:33], v[0:1]
	v_mov_b64_e32 v[28:29], v[12:13]
	v_mov_b64_e32 v[26:27], v[10:11]
	v_mov_b64_e32 v[24:25], v[8:9]
	v_mov_b64_e32 v[22:23], v[6:7]
	v_mov_b64_e32 v[20:21], v[4:5]
	v_mov_b64_e32 v[18:19], v[2:3]
	v_mov_b64_e32 v[16:17], v[0:1]
	s_mov_b32 s75, 1
	v_add_f32_e32 v196, v80, v81
	v_add_f32_e32 v196, v82, v196
	v_add_f32_e32 v196, v83, v196
	v_add_f32_e32 v196, v84, v196
	v_add_f32_e32 v196, v85, v196
	v_add_f32_e32 v196, v86, v196
	v_add_f32_e32 v196, v87, v196
	v_add_f32_e32 v196, v88, v196
	v_add_f32_e32 v196, v89, v196
	v_add_f32_e32 v196, v90, v196
	v_add_f32_e32 v196, v91, v196
	v_add_f32_e32 v196, v92, v196
	v_add_f32_e32 v196, v93, v196
	v_add_f32_e32 v196, v94, v196
	v_add_f32_e32 v196, v95, v196
	v_add_f32_e32 v196, v64, v196
	v_add_f32_e32 v196, v65, v196
	v_add_f32_e32 v196, v66, v196
	v_add_f32_e32 v196, v67, v196
	v_add_f32_e32 v196, v68, v196
	v_add_f32_e32 v196, v69, v196
	v_add_f32_e32 v196, v70, v196
	v_add_f32_e32 v196, v71, v196
	v_add_f32_e32 v196, v72, v196
	v_add_f32_e32 v196, v73, v196
	v_add_f32_e32 v196, v74, v196
	v_add_f32_e32 v196, v75, v196
	v_add_f32_e32 v196, v76, v196
	v_add_f32_e32 v196, v77, v196
	v_add_f32_e32 v196, v78, v196
	v_add_f32_e32 v196, v79, v196
	s_lshl_b32 s20, s24, 2
	s_add_i32 s20, s20, s25
	s_mul_i32 s20, s20, 0x600
	s_add_i32 s20, s20, 0x18800
	v_lshl_add_u32 v197, v177, 2, s20
	ds_write_b32 v197, v174
	ds_write_b32 v197, v175 offset:256
	ds_write_b32 v197, v176 offset:512
	ds_write_b32 v197, v177 offset:768
	ds_write_b32 v197, v178 offset:1024
	ds_write_b32 v197, v179 offset:1280
	s_waitcnt lgkmcnt(0)
	v_xor_b32_e32 v164, 0x80000000, v218
	v_xor_b32_e32 v165, 0x80000000, v218
	v_xor_b32_e32 v166, 0x80000000, v218
	v_xor_b32_e32 v167, 0x80000000, v218
	v_xor_b32_e32 v168, 0x80000000, v218
	v_xor_b32_e32 v169, 0x80000000, v218
	v_xor_b32_e32 v170, 0x80000000, v218
	v_xor_b32_e32 v171, 0x80000000, v218
	v_xor_b32_e32 v172, 0x80000000, v218
	v_xor_b32_e32 v173, 0x80000000, v218
	v_xor_b32_e32 v174, 0x80000000, v218
	v_xor_b32_e32 v175, 0x80000000, v218
	v_xor_b32_e32 v176, 0x80000000, v218
	v_xor_b32_e32 v177, 0x80000000, v218
	v_xor_b32_e32 v178, 0x80000000, v218
	v_xor_b32_e32 v179, 0x80000000, v218
	s_branch .LBB0_218

.LBB0_218:
	s_add_i32 s20, s76, 1
	s_cmp_lg_u32 s76, 2
	s_cselect_b32 s77, s20, 0
	s_lshl_b32 s46, s76, 14
	s_add_i32 s20, s46, 0xffffc000
	s_cmp_lg_u32 s76, 0
	s_cselect_b32 s47, s20, 0x8000
	s_add_i32 s20, s47, s71
	s_mov_b32 s21, m0
	s_mov_b32 m0, s20
	s_nop 0
	global_load_lds_dwordx4 v184, s[82:83]
	s_mov_b32 m0, s21
	s_addk_i32 s20, 0x2000
	s_add_u32 s79, s73, 0x800
	s_addc_u32 s81, s74, 0
	s_mov_b32 s21, m0
	s_mov_b32 m0, s20
	s_nop 0
	global_load_lds_dwordx4 v186, s[82:83]
	s_mov_b32 m0, s21
	s_add_u32 s20, s73, 0xc0800
	s_addc_u32 s21, s74, 0
	s_lshl_b32 s78, s77, 14
	s_add_i32 s76, s78, s72
	s_mov_b32 s84, m0
	s_mov_b32 m0, s76
	s_nop 0
	global_load_lds_dwordx4 v185, s[20:21]
	s_mov_b32 m0, s84
	s_addk_i32 s76, 0x2000
	s_mov_b32 s84, m0
	s_mov_b32 m0, s76
	s_nop 0
	global_load_lds_dwordx4 v187, s[20:21]
	s_mov_b32 m0, s84
	v_add_u32_e32 v104, s46, v189
	v_add_u32_e32 v100, v104, v210
	v_add_u32_e32 v105, v104, v212
	ds_read_b128 v[96:99], v100
	ds_read_b128 v[100:103], v100 offset:8192
	ds_read_b128 v[144:147], v105
	ds_read_b128 v[148:151], v105 offset:8192
	v_add_u32_e32 v105, v104, v214
	v_add_u32_e32 v104, v104, v216
	ds_read_b128 v[152:155], v105
	ds_read_b128 v[222:225], v105 offset:8192
	ds_read_b128 v[156:159], v104
	ds_read_b128 v[226:229], v104 offset:8192
	s_nop 0
	s_waitcnt lgkmcnt(7)
	v_mfma_f32_32x32x16_bf16 v[112:127], v[96:99], v[140:143], v[164:179]
	s_nop 0
	s_waitcnt lgkmcnt(6)
	v_mfma_f32_32x32x16_bf16 v[96:111], v[100:103], v[140:143], v[164:179]
	s_nop 0
	s_waitcnt lgkmcnt(5)
	v_mfma_f32_32x32x16_bf16 v[112:127], v[144:147], v[136:139], v[112:127]
	v_mov_b32_e32 v221, v196
	v_cvt_pk_bf16_f32 v144, v80, v81
	v_cvt_pk_bf16_f32 v145, v82, v83
	v_cvt_pk_bf16_f32 v146, v84, v85
	v_cvt_pk_bf16_f32 v147, v86, v87
	v_fmac_f32_e32 v221, v219, v220
	v_cvt_pk_bf16_f32 v84, v88, v89
	v_cvt_pk_bf16_f32 v85, v90, v91
	v_cvt_pk_bf16_f32 v86, v92, v93
	v_cvt_pk_bf16_f32 v87, v94, v95
	v_cvt_pk_bf16_f32 v80, v64, v65
	v_cvt_pk_bf16_f32 v81, v66, v67
	v_cvt_pk_bf16_f32 v82, v68, v69
	v_cvt_pk_bf16_f32 v83, v70, v71
	v_cvt_pk_bf16_f32 v64, v72, v73
	v_cvt_pk_bf16_f32 v65, v74, v75
	v_cvt_pk_bf16_f32 v66, v76, v77
	v_cvt_pk_bf16_f32 v67, v78, v79
	s_waitcnt lgkmcnt(4)
	v_mfma_f32_32x32x16_bf16 v[96:111], v[148:151], v[136:139], v[96:111]
	v_add_u32_e32 v196, s47, v217
	s_waitcnt lgkmcnt(3)
	v_mfma_f32_32x32x16_bf16 v[112:127], v[152:155], v[132:135], v[112:127]
	ds_read_b64_tr_b16 v[72:73], v196
	ds_read_b64_tr_b16 v[88:89], v196 offset:512
	ds_read_b64_tr_b16 v[152:153], v196 offset:1024
	ds_read_b64_tr_b16 v[230:231], v196 offset:1536
	ds_read_b64_tr_b16 v[74:75], v196 offset:2048
	ds_read_b64_tr_b16 v[90:91], v196 offset:2560
	ds_read_b64_tr_b16 v[154:155], v196 offset:3072
	ds_read_b64_tr_b16 v[232:233], v196 offset:3584
	s_waitcnt lgkmcnt(10)
	v_mfma_f32_32x32x16_bf16 v[96:111], v[222:225], v[132:135], v[96:111]
	s_waitcnt lgkmcnt(9)
	v_mfma_f32_32x32x16_bf16 v[112:127], v[156:159], v[128:131], v[112:127]
	ds_read_b64_tr_b16 v[234:235], v196 offset:4096
	ds_read_b64_tr_b16 v[238:239], v196 offset:4608
	ds_read_b64_tr_b16 v[242:243], v196 offset:5120
	ds_read_b64_tr_b16 v[156:157], v196 offset:5632
	ds_read_b64_tr_b16 v[236:237], v196 offset:6144
	ds_read_b64_tr_b16 v[240:241], v196 offset:6656
	ds_read_b64_tr_b16 v[244:245], v196 offset:7168
	ds_read_b64_tr_b16 v[158:159], v196 offset:7680
	ds_read_b64_tr_b16 v[148:149], v196 offset:8192
	ds_read_b64_tr_b16 v[92:93], v196 offset:8704
	ds_read_b64_tr_b16 v[76:77], v196 offset:9216
	ds_read_b64_tr_b16 v[68:69], v196 offset:9728
	ds_read_b64_tr_b16 v[150:151], v196 offset:10240
	ds_read_b64_tr_b16 v[94:95], v196 offset:10752
	ds_read_b64_tr_b16 v[78:79], v196 offset:11264
	ds_read_b64_tr_b16 v[70:71], v196 offset:11776
	s_waitcnt lgkmcnt(14)
	v_mfma_f32_32x32x16_bf16 v[96:111], v[226:229], v[128:131], v[96:111]
	v_mfma_f32_32x32x16_bf16 v[0:15], v[144:147], v[72:75], v[0:15]
	v_max3_f32 v72, v112, v113, v114
	v_max3_f32 v72, v72, v115, v116
	v_max3_f32 v72, v72, v117, v118
	v_max3_f32 v72, v72, v119, v120
	v_mfma_f32_32x32x16_bf16 v[48:63], v[144:147], v[88:91], v[48:63]
	v_max3_f32 v72, v72, v121, v122
	v_max3_f32 v72, v72, v123, v124
	v_max3_f32 v72, v72, v125, v126
	s_nop 2
	v_max3_f32 v72, v72, v127, v96
	v_mfma_f32_32x32x16_bf16 v[32:47], v[144:147], v[152:155], v[32:47]
	v_max3_f32 v72, v72, v97, v98
	v_max3_f32 v72, v72, v99, v100
	v_max3_f32 v72, v72, v101, v102
	v_max3_f32 v72, v72, v103, v104
	v_mfma_f32_32x32x16_bf16 v[16:31], v[144:147], v[230:233], v[16:31]
	v_max_f32_e32 v72, v72, v72
	v_max_f32_e32 v73, v105, v105
	v_max_f32_e32 v72, v72, v73
	v_max3_f32 v72, v72, v106, v107
	v_max3_f32 v72, v72, v108, v109
	v_max3_f32 v197, v72, v110, v111
	ds_read_b64_tr_b16 v[152:153], v196 offset:12288
	ds_read_b64_tr_b16 v[144:145], v196 offset:12800
	ds_read_b64_tr_b16 v[88:89], v196 offset:13312
	ds_read_b64_tr_b16 v[72:73], v196 offset:13824
	ds_read_b64_tr_b16 v[154:155], v196 offset:14336
	ds_read_b64_tr_b16 v[146:147], v196 offset:14848
	ds_read_b64_tr_b16 v[90:91], v196 offset:15360
	ds_read_b64_tr_b16 v[74:75], v196 offset:15872
	v_cmp_ge_f32_e32 vcc, s6, v197
	s_cmp_eq_u64 vcc, exec
	s_cbranch_scc0 .Latt_rare_1
	v_mov_b32_e32 v220, v218
	v_mov_b32_e32 v218, 1.0
.Latt_back_1:
	s_waitcnt lgkmcnt(14)
	v_mfma_f32_32x32x16_bf16 v[0:15], v[84:87], v[234:237], v[0:15]
	v_mfma_f32_32x32x16_bf16 v[48:63], v[84:87], v[238:241], v[48:63]
	v_mfma_f32_32x32x16_bf16 v[32:47], v[84:87], v[242:245], v[32:47]
	v_mfma_f32_32x32x16_bf16 v[16:31], v[84:87], v[156:159], v[16:31]
	s_waitcnt lgkmcnt(11)
	v_mfma_f32_32x32x16_bf16 v[0:15], v[80:83], v[148:151], v[0:15]
	s_waitcnt lgkmcnt(10)
	v_mfma_f32_32x32x16_bf16 v[48:63], v[80:83], v[92:95], v[48:63]
	v_exp_f32_e32 v112, v112
	v_exp_f32_e32 v113, v113
	v_exp_f32_e32 v114, v114
	v_exp_f32_e32 v115, v115
	v_add_f32_e32 v196, v112, v113
	v_add_f32_e32 v196, v114, v196
	v_add_f32_e32 v196, v115, v196
	s_waitcnt lgkmcnt(9)
	v_mfma_f32_32x32x16_bf16 v[32:47], v[80:83], v[76:79], v[32:47]
	v_exp_f32_e32 v116, v116
	v_exp_f32_e32 v117, v117
	v_exp_f32_e32 v118, v118
	v_exp_f32_e32 v119, v119
	v_add_f32_e32 v196, v116, v196
	v_add_f32_e32 v196, v117, v196
	v_add_f32_e32 v196, v118, v196
	v_add_f32_e32 v196, v119, v196
	s_waitcnt lgkmcnt(8)
	v_mfma_f32_32x32x16_bf16 v[16:31], v[80:83], v[68:71], v[16:31]
	v_exp_f32_e32 v120, v120
	v_exp_f32_e32 v121, v121
	v_exp_f32_e32 v122, v122
	v_exp_f32_e32 v123, v123
	v_add_f32_e32 v196, v120, v196
	v_add_f32_e32 v196, v121, v196
	v_add_f32_e32 v196, v122, v196
	v_add_f32_e32 v196, v123, v196
	s_waitcnt lgkmcnt(3)
	v_mfma_f32_32x32x16_bf16 v[0:15], v[64:67], v[152:155], v[0:15]
	v_exp_f32_e32 v124, v124
	v_exp_f32_e32 v125, v125
	v_exp_f32_e32 v126, v126
	v_exp_f32_e32 v127, v127
	v_add_f32_e32 v196, v124, v196
	v_add_f32_e32 v196, v125, v196
	v_add_f32_e32 v196, v126, v196
	v_add_f32_e32 v196, v127, v196
	s_waitcnt lgkmcnt(2)
	v_mfma_f32_32x32x16_bf16 v[48:63], v[64:67], v[144:147], v[48:63]
	v_exp_f32_e32 v96, v96
	v_exp_f32_e32 v97, v97
	v_exp_f32_e32 v98, v98
	v_exp_f32_e32 v99, v99
	v_exp_f32_e32 v100, v100
	v_add_f32_e32 v196, v96, v196
	v_add_f32_e32 v196, v97, v196
	v_add_f32_e32 v196, v98, v196
	v_add_f32_e32 v196, v99, v196
	v_add_f32_e32 v196, v100, v196
	s_waitcnt lgkmcnt(1)
	v_mfma_f32_32x32x16_bf16 v[32:47], v[64:67], v[88:91], v[32:47]
	v_exp_f32_e32 v101, v101
	v_exp_f32_e32 v102, v102
	v_exp_f32_e32 v103, v103
	v_exp_f32_e32 v104, v104
	v_exp_f32_e32 v105, v105
	v_add_f32_e32 v196, v101, v196
	v_add_f32_e32 v196, v102, v196
	v_add_f32_e32 v196, v103, v196
	v_add_f32_e32 v196, v104, v196
	v_add_f32_e32 v196, v105, v196
	s_waitcnt lgkmcnt(0)
	v_mfma_f32_32x32x16_bf16 v[16:31], v[64:67], v[72:75], v[16:31]
	v_exp_f32_e32 v106, v106
	v_exp_f32_e32 v107, v107
	v_exp_f32_e32 v108, v108
	v_exp_f32_e32 v109, v109
	v_exp_f32_e32 v110, v110
	v_exp_f32_e32 v111, v111
	v_add_f32_e32 v196, v106, v196
	v_add_f32_e32 v196, v107, v196
	v_add_f32_e32 v196, v108, v196
	v_add_f32_e32 v196, v109, v196
	v_add_f32_e32 v196, v110, v196
	v_add_f32_e32 v196, v111, v196
	v_cmp_gt_f32_e32 vcc, 1.0, v218
	s_cbranch_vccz .LBB0_222
	s_and_saveexec_b64 s[20:21], s[38:39]
	ds_write_b32 v182, v218 offset:128
	s_or_b64 exec, exec, s[20:21]
	s_waitcnt lgkmcnt(0)
	v_add_u32_e32 v76, s70, v162
	ds_read_b128 v[64:67], v76 offset:224
	ds_read_b128 v[68:71], v76 offset:192
	ds_read_b128 v[72:75], v76 offset:160
	ds_read_b128 v[76:79], v76 offset:128
	s_waitcnt lgkmcnt(3)
	v_pk_mul_f32 v[12:13], v[12:13], v[64:65]
	s_waitcnt lgkmcnt(2)
	v_pk_mul_f32 v[8:9], v[8:9], v[68:69]
	s_waitcnt lgkmcnt(1)
	v_pk_mul_f32 v[4:5], v[4:5], v[72:73]
	v_pk_mul_f32 v[14:15], v[14:15], v[66:67]
	v_pk_mul_f32 v[10:11], v[10:11], v[70:71]
	v_pk_mul_f32 v[6:7], v[6:7], v[74:75]
	s_waitcnt lgkmcnt(0)
	v_pk_mul_f32 v[2:3], v[2:3], v[78:79]
	v_pk_mul_f32 v[0:1], v[0:1], v[76:77]
	v_pk_mul_f32 v[60:61], v[60:61], v[64:65]
	v_pk_mul_f32 v[56:57], v[56:57], v[68:69]
	v_pk_mul_f32 v[52:53], v[52:53], v[72:73]
	v_pk_mul_f32 v[62:63], v[62:63], v[66:67]
	v_pk_mul_f32 v[58:59], v[58:59], v[70:71]
	v_pk_mul_f32 v[54:55], v[54:55], v[74:75]
	v_pk_mul_f32 v[50:51], v[50:51], v[78:79]
	v_pk_mul_f32 v[48:49], v[48:49], v[76:77]
	v_pk_mul_f32 v[44:45], v[44:45], v[64:65]
	v_pk_mul_f32 v[40:41], v[40:41], v[68:69]
	v_pk_mul_f32 v[36:37], v[36:37], v[72:73]
	v_pk_mul_f32 v[46:47], v[46:47], v[66:67]
	v_pk_mul_f32 v[42:43], v[42:43], v[70:71]
	v_pk_mul_f32 v[38:39], v[38:39], v[74:75]
	v_pk_mul_f32 v[34:35], v[34:35], v[78:79]
	v_pk_mul_f32 v[32:33], v[32:33], v[76:77]
	v_pk_mul_f32 v[28:29], v[28:29], v[64:65]
	v_pk_mul_f32 v[24:25], v[24:25], v[68:69]
	v_pk_mul_f32 v[20:21], v[20:21], v[72:73]
	v_pk_mul_f32 v[30:31], v[30:31], v[66:67]
	v_pk_mul_f32 v[26:27], v[26:27], v[70:71]
	v_pk_mul_f32 v[22:23], v[22:23], v[74:75]
	v_pk_mul_f32 v[18:19], v[18:19], v[78:79]
	v_pk_mul_f32 v[16:17], v[16:17], v[76:77]

.LBB0_226:
	s_add_i32 s20, s77, 1
	s_cmp_lg_u32 s77, 2
	s_cselect_b32 s76, s20, 0
	s_lshl_b32 s20, s76, 14
	s_add_i32 s46, s20, s72
	s_add_i32 s47, s46, 0x2000
	s_add_u32 s20, s79, 0x180000
	s_addc_u32 s21, s81, 0
	s_mov_b32 s77, m0
	s_mov_b32 m0, s46
	s_nop 0
	global_load_lds_dwordx4 v185, s[20:21]
	s_mov_b32 m0, s77
	s_mov_b32 s46, m0
	s_mov_b32 m0, s47
	s_nop 0
	global_load_lds_dwordx4 v187, s[20:21]
	s_mov_b32 m0, s46
	v_add_u32_e32 v72, s78, v189
	v_add_u32_e32 v68, v72, v210
	v_add_u32_e32 v73, v72, v212
	ds_read_b128 v[64:67], v68
	ds_read_b128 v[68:71], v68 offset:8192
	ds_read_b128 v[144:147], v73
	ds_read_b128 v[148:151], v73 offset:8192
	v_add_u32_e32 v73, v72, v214
	v_add_u32_e32 v72, v72, v216
	ds_read_b128 v[152:155], v73
	ds_read_b128 v[222:225], v73 offset:8192
	ds_read_b128 v[156:159], v72
	ds_read_b128 v[226:229], v72 offset:8192
	s_nop 0
	s_waitcnt lgkmcnt(7)
	v_mfma_f32_32x32x16_bf16 v[80:95], v[64:67], v[140:143], v[164:179]
	s_nop 0
	s_waitcnt lgkmcnt(6)
	v_mfma_f32_32x32x16_bf16 v[64:79], v[68:71], v[140:143], v[164:179]
	s_nop 0
	s_waitcnt lgkmcnt(5)
	v_mfma_f32_32x32x16_bf16 v[80:95], v[144:147], v[136:139], v[80:95]
	v_mov_b32_e32 v219, v196
	v_cvt_pk_bf16_f32 v144, v112, v113
	v_cvt_pk_bf16_f32 v145, v114, v115
	v_cvt_pk_bf16_f32 v146, v116, v117
	v_cvt_pk_bf16_f32 v147, v118, v119
	v_fmac_f32_e32 v219, v221, v218
	v_cvt_pk_bf16_f32 v116, v120, v121
	v_cvt_pk_bf16_f32 v117, v122, v123
	v_cvt_pk_bf16_f32 v118, v124, v125
	v_cvt_pk_bf16_f32 v119, v126, v127
	v_cvt_pk_bf16_f32 v112, v96, v97
	v_cvt_pk_bf16_f32 v113, v98, v99
	v_cvt_pk_bf16_f32 v114, v100, v101
	v_cvt_pk_bf16_f32 v115, v102, v103
	v_cvt_pk_bf16_f32 v96, v104, v105
	v_cvt_pk_bf16_f32 v97, v106, v107
	v_cvt_pk_bf16_f32 v98, v108, v109
	v_cvt_pk_bf16_f32 v99, v110, v111
	s_waitcnt lgkmcnt(4)
	v_mfma_f32_32x32x16_bf16 v[64:79], v[148:151], v[136:139], v[64:79]
	v_add_u32_e32 v196, s86, v217
	s_waitcnt lgkmcnt(3)
	v_mfma_f32_32x32x16_bf16 v[80:95], v[152:155], v[132:135], v[80:95]
	ds_read_b64_tr_b16 v[104:105], v196
	ds_read_b64_tr_b16 v[120:121], v196 offset:512
	ds_read_b64_tr_b16 v[152:153], v196 offset:1024
	ds_read_b64_tr_b16 v[230:231], v196 offset:1536
	ds_read_b64_tr_b16 v[106:107], v196 offset:2048
	ds_read_b64_tr_b16 v[122:123], v196 offset:2560
	ds_read_b64_tr_b16 v[154:155], v196 offset:3072
	ds_read_b64_tr_b16 v[232:233], v196 offset:3584
	s_waitcnt lgkmcnt(10)
	v_mfma_f32_32x32x16_bf16 v[64:79], v[222:225], v[132:135], v[64:79]
	s_waitcnt lgkmcnt(9)
	v_mfma_f32_32x32x16_bf16 v[80:95], v[156:159], v[128:131], v[80:95]
	ds_read_b64_tr_b16 v[234:235], v196 offset:4096
	ds_read_b64_tr_b16 v[238:239], v196 offset:4608
	ds_read_b64_tr_b16 v[242:243], v196 offset:5120
	ds_read_b64_tr_b16 v[156:157], v196 offset:5632
	ds_read_b64_tr_b16 v[236:237], v196 offset:6144
	ds_read_b64_tr_b16 v[240:241], v196 offset:6656
	ds_read_b64_tr_b16 v[244:245], v196 offset:7168
	ds_read_b64_tr_b16 v[158:159], v196 offset:7680
	ds_read_b64_tr_b16 v[148:149], v196 offset:8192
	ds_read_b64_tr_b16 v[124:125], v196 offset:8704
	ds_read_b64_tr_b16 v[108:109], v196 offset:9216
	ds_read_b64_tr_b16 v[100:101], v196 offset:9728
	ds_read_b64_tr_b16 v[150:151], v196 offset:10240
	ds_read_b64_tr_b16 v[126:127], v196 offset:10752
	ds_read_b64_tr_b16 v[110:111], v196 offset:11264
	ds_read_b64_tr_b16 v[102:103], v196 offset:11776
	s_waitcnt lgkmcnt(14)
	v_mfma_f32_32x32x16_bf16 v[64:79], v[226:229], v[128:131], v[64:79]
	v_mfma_f32_32x32x16_bf16 v[0:15], v[144:147], v[104:107], v[0:15]
	v_max3_f32 v104, v80, v81, v82
	v_max3_f32 v104, v104, v83, v84
	v_max3_f32 v104, v104, v85, v86
	v_max3_f32 v104, v104, v87, v88
	v_mfma_f32_32x32x16_bf16 v[48:63], v[144:147], v[120:123], v[48:63]
	v_max3_f32 v104, v104, v89, v90
	v_max3_f32 v104, v104, v91, v92
	v_max3_f32 v104, v104, v93, v94
	s_nop 2
	v_max3_f32 v104, v104, v95, v64
	v_mfma_f32_32x32x16_bf16 v[32:47], v[144:147], v[152:155], v[32:47]
	v_max3_f32 v104, v104, v65, v66
	v_max3_f32 v104, v104, v67, v68
	v_max3_f32 v104, v104, v69, v70
	v_max3_f32 v104, v104, v71, v72
	v_mfma_f32_32x32x16_bf16 v[16:31], v[144:147], v[230:233], v[16:31]
	v_max_f32_e32 v104, v104, v104
	v_max_f32_e32 v105, v73, v73
	v_max_f32_e32 v104, v104, v105
	v_max3_f32 v104, v104, v74, v75
	v_max3_f32 v104, v104, v76, v77
	v_max3_f32 v197, v104, v78, v79
	ds_read_b64_tr_b16 v[152:153], v196 offset:12288
	ds_read_b64_tr_b16 v[144:145], v196 offset:12800
	ds_read_b64_tr_b16 v[120:121], v196 offset:13312
	ds_read_b64_tr_b16 v[104:105], v196 offset:13824
	ds_read_b64_tr_b16 v[154:155], v196 offset:14336
	ds_read_b64_tr_b16 v[146:147], v196 offset:14848
	ds_read_b64_tr_b16 v[122:123], v196 offset:15360
	ds_read_b64_tr_b16 v[106:107], v196 offset:15872
	v_cmp_ge_f32_e32 vcc, s6, v197
	s_cmp_eq_u64 vcc, exec
	s_cbranch_scc0 .Latt_rare_2
	v_mov_b32_e32 v218, v220
	v_mov_b32_e32 v220, 1.0
.Latt_back_2:
	s_waitcnt lgkmcnt(14)
	v_mfma_f32_32x32x16_bf16 v[0:15], v[116:119], v[234:237], v[0:15]
	v_mfma_f32_32x32x16_bf16 v[48:63], v[116:119], v[238:241], v[48:63]
	v_mfma_f32_32x32x16_bf16 v[32:47], v[116:119], v[242:245], v[32:47]
	v_mfma_f32_32x32x16_bf16 v[16:31], v[116:119], v[156:159], v[16:31]
	s_waitcnt lgkmcnt(11)
	v_mfma_f32_32x32x16_bf16 v[0:15], v[112:115], v[148:151], v[0:15]
	s_waitcnt lgkmcnt(10)
	v_mfma_f32_32x32x16_bf16 v[48:63], v[112:115], v[124:127], v[48:63]
	v_exp_f32_e32 v80, v80
	v_exp_f32_e32 v81, v81
	v_exp_f32_e32 v82, v82
	v_exp_f32_e32 v83, v83
	v_add_f32_e32 v196, v80, v81
	v_add_f32_e32 v196, v82, v196
	v_add_f32_e32 v196, v83, v196
	s_waitcnt lgkmcnt(9)
	v_mfma_f32_32x32x16_bf16 v[32:47], v[112:115], v[108:111], v[32:47]
	v_exp_f32_e32 v84, v84
	v_exp_f32_e32 v85, v85
	v_exp_f32_e32 v86, v86
	v_exp_f32_e32 v87, v87
	v_add_f32_e32 v196, v84, v196
	v_add_f32_e32 v196, v85, v196
	v_add_f32_e32 v196, v86, v196
	v_add_f32_e32 v196, v87, v196
	s_waitcnt lgkmcnt(8)
	v_mfma_f32_32x32x16_bf16 v[16:31], v[112:115], v[100:103], v[16:31]
	v_exp_f32_e32 v88, v88
	v_exp_f32_e32 v89, v89
	v_exp_f32_e32 v90, v90
	v_exp_f32_e32 v91, v91
	v_add_f32_e32 v196, v88, v196
	v_add_f32_e32 v196, v89, v196
	v_add_f32_e32 v196, v90, v196
	v_add_f32_e32 v196, v91, v196
	s_waitcnt lgkmcnt(3)
	v_mfma_f32_32x32x16_bf16 v[0:15], v[96:99], v[152:155], v[0:15]
	v_exp_f32_e32 v92, v92
	v_exp_f32_e32 v93, v93
	v_exp_f32_e32 v94, v94
	v_exp_f32_e32 v95, v95
	v_add_f32_e32 v196, v92, v196
	v_add_f32_e32 v196, v93, v196
	v_add_f32_e32 v196, v94, v196
	v_add_f32_e32 v196, v95, v196
	s_waitcnt lgkmcnt(2)
	v_mfma_f32_32x32x16_bf16 v[48:63], v[96:99], v[144:147], v[48:63]
	v_exp_f32_e32 v64, v64
	v_exp_f32_e32 v65, v65
	v_exp_f32_e32 v66, v66
	v_exp_f32_e32 v67, v67
	v_exp_f32_e32 v68, v68
	v_add_f32_e32 v196, v64, v196
	v_add_f32_e32 v196, v65, v196
	v_add_f32_e32 v196, v66, v196
	v_add_f32_e32 v196, v67, v196
	v_add_f32_e32 v196, v68, v196
	s_waitcnt lgkmcnt(1)
	v_mfma_f32_32x32x16_bf16 v[32:47], v[96:99], v[120:123], v[32:47]
	v_exp_f32_e32 v69, v69
	v_exp_f32_e32 v70, v70
	v_exp_f32_e32 v71, v71
	v_exp_f32_e32 v72, v72
	v_exp_f32_e32 v73, v73
	v_add_f32_e32 v196, v69, v196
	v_add_f32_e32 v196, v70, v196
	v_add_f32_e32 v196, v71, v196
	v_add_f32_e32 v196, v72, v196
	v_add_f32_e32 v196, v73, v196
	s_waitcnt lgkmcnt(0)
	v_mfma_f32_32x32x16_bf16 v[16:31], v[96:99], v[104:107], v[16:31]
	v_exp_f32_e32 v74, v74
	v_exp_f32_e32 v75, v75
	v_exp_f32_e32 v76, v76
	v_exp_f32_e32 v77, v77
	v_exp_f32_e32 v78, v78
	v_exp_f32_e32 v79, v79
	v_add_f32_e32 v196, v74, v196
	v_add_f32_e32 v196, v75, v196
	v_add_f32_e32 v196, v76, v196
	v_add_f32_e32 v196, v77, v196
	v_add_f32_e32 v196, v78, v196
	v_add_f32_e32 v196, v79, v196
	v_cmp_gt_f32_e32 vcc, 1.0, v220
	s_cbranch_vccz .LBB0_230
	s_and_saveexec_b64 s[20:21], s[38:39]
	ds_write_b32 v182, v220 offset:128
	s_or_b64 exec, exec, s[20:21]
	s_waitcnt lgkmcnt(0)
	v_add_u32_e32 v108, s70, v162
	ds_read_b128 v[96:99], v108 offset:224
	ds_read_b128 v[100:103], v108 offset:192
	ds_read_b128 v[104:107], v108 offset:160
	ds_read_b128 v[108:111], v108 offset:128
	s_waitcnt lgkmcnt(3)
	v_pk_mul_f32 v[12:13], v[12:13], v[96:97]
	s_waitcnt lgkmcnt(2)
	v_pk_mul_f32 v[8:9], v[8:9], v[100:101]
	s_waitcnt lgkmcnt(1)
	v_pk_mul_f32 v[4:5], v[4:5], v[104:105]
	v_pk_mul_f32 v[14:15], v[14:15], v[98:99]
	v_pk_mul_f32 v[10:11], v[10:11], v[102:103]
	v_pk_mul_f32 v[6:7], v[6:7], v[106:107]
	s_waitcnt lgkmcnt(0)
	v_pk_mul_f32 v[2:3], v[2:3], v[110:111]
	v_pk_mul_f32 v[0:1], v[0:1], v[108:109]
	v_pk_mul_f32 v[60:61], v[60:61], v[96:97]
	v_pk_mul_f32 v[56:57], v[56:57], v[100:101]
	v_pk_mul_f32 v[52:53], v[52:53], v[104:105]
	v_pk_mul_f32 v[62:63], v[62:63], v[98:99]
	v_pk_mul_f32 v[58:59], v[58:59], v[102:103]
	v_pk_mul_f32 v[54:55], v[54:55], v[106:107]
	v_pk_mul_f32 v[50:51], v[50:51], v[110:111]
	v_pk_mul_f32 v[48:49], v[48:49], v[108:109]
	v_pk_mul_f32 v[44:45], v[44:45], v[96:97]
	v_pk_mul_f32 v[40:41], v[40:41], v[100:101]
	v_pk_mul_f32 v[36:37], v[36:37], v[104:105]
	v_pk_mul_f32 v[46:47], v[46:47], v[98:99]
	v_pk_mul_f32 v[42:43], v[42:43], v[102:103]
	v_pk_mul_f32 v[38:39], v[38:39], v[106:107]
	v_pk_mul_f32 v[34:35], v[34:35], v[110:111]
	v_pk_mul_f32 v[32:33], v[32:33], v[108:109]
	v_pk_mul_f32 v[28:29], v[28:29], v[96:97]
	v_pk_mul_f32 v[24:25], v[24:25], v[100:101]
	v_pk_mul_f32 v[20:21], v[20:21], v[104:105]
	v_pk_mul_f32 v[30:31], v[30:31], v[98:99]
	v_pk_mul_f32 v[26:27], v[26:27], v[102:103]
	v_pk_mul_f32 v[22:23], v[22:23], v[106:107]
	v_pk_mul_f32 v[18:19], v[18:19], v[110:111]
	v_pk_mul_f32 v[16:17], v[16:17], v[108:109]

.LBB0_234:
	ds_read_b128 v[96:99], v188
	ds_read_b128 v[100:103], v188 offset:8192
	ds_read_b128 v[144:147], v211
	ds_read_b128 v[148:151], v211 offset:8192
	ds_read_b128 v[152:155], v213
	ds_read_b128 v[156:159], v213 offset:8192
	ds_read_b128 v[184:187], v215
	ds_read_b128 v[210:213], v215 offset:8192
	s_nop 0
	s_waitcnt lgkmcnt(7)
	v_mfma_f32_32x32x16_bf16 v[112:127], v[96:99], v[140:143], v[164:179]
	s_nop 0
	s_waitcnt lgkmcnt(6)
	v_mfma_f32_32x32x16_bf16 v[96:111], v[100:103], v[140:143], v[164:179]
	s_nop 0
	s_waitcnt lgkmcnt(5)
	v_mfma_f32_32x32x16_bf16 v[112:127], v[144:147], v[136:139], v[112:127]
	v_mov_b32_e32 v144, v196
	v_cvt_pk_bf16_f32 v214, v80, v81
	v_cvt_pk_bf16_f32 v215, v82, v83
	v_cvt_pk_bf16_f32 v216, v84, v85
	v_cvt_pk_bf16_f32 v217, v86, v87
	v_fmac_f32_e32 v144, v219, v220
	v_cvt_pk_bf16_f32 v84, v88, v89
	v_cvt_pk_bf16_f32 v85, v90, v91
	v_cvt_pk_bf16_f32 v86, v92, v93
	v_cvt_pk_bf16_f32 v87, v94, v95
	v_cvt_pk_bf16_f32 v80, v64, v65
	v_cvt_pk_bf16_f32 v81, v66, v67
	v_cvt_pk_bf16_f32 v82, v68, v69
	v_cvt_pk_bf16_f32 v83, v70, v71
	v_cvt_pk_bf16_f32 v64, v72, v73
	v_cvt_pk_bf16_f32 v65, v74, v75
	v_cvt_pk_bf16_f32 v66, v76, v77
	v_cvt_pk_bf16_f32 v67, v78, v79
	s_cmp_lg_u32 0, -1
	s_cselect_b32 s20, 0, 0
	v_add_u32_e32 v145, s20, v183
	v_add_u32_e32 v68, 0x14000, v145
	ds_read_b64_tr_b16 v[72:73], v68
	v_add_u32_e32 v68, 0x14800, v145
	s_waitcnt lgkmcnt(4)
	v_mfma_f32_32x32x16_bf16 v[112:127], v[152:155], v[132:135], v[112:127]
	ds_read_b64_tr_b16 v[74:75], v68
	v_add_u32_e32 v68, 0x14200, v145
	ds_read_b64_tr_b16 v[88:89], v68
	v_add_u32_e32 v68, 0x14a00, v145
	ds_read_b64_tr_b16 v[90:91], v68
	v_add_u32_e32 v68, 0x14400, v145
	ds_read_b64_tr_b16 v[152:153], v68
	v_mfma_f32_32x32x16_bf16 v[96:111], v[148:151], v[136:139], v[96:111]
	v_add_u32_e32 v68, 0x14c00, v145
	ds_read_b64_tr_b16 v[154:155], v68
	v_add_u32_e32 v68, 0x14600, v145
	ds_read_b64_tr_b16 v[220:221], v68
	v_add_u32_e32 v68, 0x14e00, v145
	ds_read_b64_tr_b16 v[222:223], v68
	v_add_u32_e32 v68, 0x15000, v145
	s_waitcnt lgkmcnt(9)
	v_mfma_f32_32x32x16_bf16 v[112:127], v[184:187], v[128:131], v[112:127]
	ds_read_b64_tr_b16 v[184:185], v68
	v_add_u32_e32 v68, 0x15800, v145
	ds_read_b64_tr_b16 v[186:187], v68
	v_add_u32_e32 v68, 0x15200, v145
	ds_read_b64_tr_b16 v[224:225], v68
	v_add_u32_e32 v68, 0x15a00, v145
	ds_read_b64_tr_b16 v[226:227], v68
	v_mfma_f32_32x32x16_bf16 v[96:111], v[156:159], v[132:135], v[96:111]
	v_add_u32_e32 v68, 0x15400, v145
	ds_read_b64_tr_b16 v[146:147], v68
	v_add_u32_e32 v68, 0x15c00, v145
	ds_read_b64_tr_b16 v[148:149], v68
	v_add_u32_e32 v68, 0x15600, v145
	ds_read_b64_tr_b16 v[140:141], v68
	v_add_u32_e32 v68, 0x15e00, v145
	ds_read_b64_tr_b16 v[142:143], v68
	v_add_u32_e32 v68, 0x16000, v145
	ds_read_b64_tr_b16 v[132:133], v68
	v_add_u32_e32 v68, 0x16800, v145
	ds_read_b64_tr_b16 v[134:135], v68
	v_add_u32_e32 v68, 0x16200, v145
	ds_read_b64_tr_b16 v[92:93], v68
	v_add_u32_e32 v68, 0x16a00, v145
	s_waitcnt lgkmcnt(14)
	v_mfma_f32_32x32x16_bf16 v[96:111], v[210:213], v[128:131], v[96:111]
	ds_read_b64_tr_b16 v[94:95], v68
	v_add_u32_e32 v68, 0x16400, v145
	ds_read_b64_tr_b16 v[76:77], v68
	v_add_u32_e32 v68, 0x16c00, v145
	ds_read_b64_tr_b16 v[78:79], v68
	v_add_u32_e32 v68, 0x16600, v145
	v_add_u32_e32 v70, 0x16e00, v145
	ds_read_b64_tr_b16 v[68:69], v68
	ds_read_b64_tr_b16 v[70:71], v70
	v_mfma_f32_32x32x16_bf16 v[0:15], v[214:217], v[72:75], v[0:15]
	v_max3_f32 v72, v112, v113, v114
	v_max3_f32 v72, v72, v115, v116
	v_max3_f32 v72, v72, v117, v118
	v_max3_f32 v72, v72, v119, v120
	v_mfma_f32_32x32x16_bf16 v[48:63], v[214:217], v[88:91], v[48:63]
	v_max3_f32 v72, v72, v121, v122
	v_max3_f32 v72, v72, v123, v124
	v_max3_f32 v72, v72, v125, v126
	v_max3_f32 v72, v72, v127, v96
	s_waitcnt lgkmcnt(14)
	v_mfma_f32_32x32x16_bf16 v[32:47], v[214:217], v[152:155], v[32:47]
	v_max3_f32 v72, v72, v97, v98
	v_max3_f32 v72, v72, v99, v100
	v_max3_f32 v72, v72, v101, v102
	v_max3_f32 v72, v72, v103, v104
	v_mfma_f32_32x32x16_bf16 v[16:31], v[214:217], v[220:223], v[16:31]
	v_max_f32_e32 v72, v72, v72
	v_max_f32_e32 v73, v105, v105
	v_max_f32_e32 v72, v72, v73
	v_max3_f32 v72, v72, v106, v107
	v_max3_f32 v72, v72, v108, v109
	v_max3_f32 v150, v72, v110, v111
	v_add_u32_e32 v72, 0x17000, v145
	ds_read_b64_tr_b16 v[136:137], v72
	v_add_u32_e32 v72, 0x17800, v145
	ds_read_b64_tr_b16 v[138:139], v72
	v_add_u32_e32 v72, 0x17200, v145
	ds_read_b64_tr_b16 v[128:129], v72
	v_add_u32_e32 v72, 0x17a00, v145
	ds_read_b64_tr_b16 v[130:131], v72
	v_add_u32_e32 v72, 0x17400, v145
	ds_read_b64_tr_b16 v[88:89], v72
	v_add_u32_e32 v72, 0x17c00, v145
	ds_read_b64_tr_b16 v[90:91], v72
	v_add_u32_e32 v72, 0x17600, v145
	v_add_u32_e32 v74, 0x17e00, v145
	ds_read_b64_tr_b16 v[72:73], v72
	ds_read_b64_tr_b16 v[74:75], v74
	v_cmp_ge_f32_e32 vcc, s6, v150
	s_cmp_eq_u64 vcc, exec
	s_cbranch_scc0 .Latt_rare_3
	v_mov_b32_e32 v145, 1.0
; __device__ __forceinline__ void attn_unit(const bf16* __restrict__ proj, bf16* __restrict__ cat, int b, int h, int qb, float lam, float oscale, const float* __restrict__ subln, const float* __restrict__ cw, char* lds) {
;     ...
;   { float ps = 0.f;
; #pragma unroll
;     for (int r = 0; r < 16; ++r) ps += pB0[r];
; #pragma unroll
;     for (int r = 0; r < 16; ++r) ps += pB1[r];
.Latt_back_3:
	v_mfma_f32_32x32x16_bf16 v[0:15], v[84:87], v[184:187], v[0:15]
	s_waitcnt lgkmcnt(14)
	v_mfma_f32_32x32x16_bf16 v[48:63], v[84:87], v[224:227], v[48:63]
	v_mfma_f32_32x32x16_bf16 v[32:47], v[84:87], v[146:149], v[32:47]
	v_mfma_f32_32x32x16_bf16 v[16:31], v[84:87], v[140:143], v[16:31]
	v_mfma_f32_32x32x16_bf16 v[0:15], v[80:83], v[132:135], v[0:15]
	s_waitcnt lgkmcnt(12)
	v_mfma_f32_32x32x16_bf16 v[48:63], v[80:83], v[92:95], v[48:63]
	v_exp_f32_e32 v112, v112
	v_exp_f32_e32 v113, v113
	v_exp_f32_e32 v114, v114
	v_exp_f32_e32 v115, v115
	s_waitcnt lgkmcnt(10)
	v_mfma_f32_32x32x16_bf16 v[32:47], v[80:83], v[76:79], v[32:47]
	v_exp_f32_e32 v116, v116
	v_exp_f32_e32 v117, v117
	v_exp_f32_e32 v118, v118
	v_exp_f32_e32 v119, v119
	s_waitcnt lgkmcnt(8)
	v_mfma_f32_32x32x16_bf16 v[16:31], v[80:83], v[68:71], v[16:31]
	v_exp_f32_e32 v120, v120
	v_exp_f32_e32 v121, v121
	v_exp_f32_e32 v122, v122
	v_exp_f32_e32 v123, v123
	s_waitcnt lgkmcnt(6)
	v_mfma_f32_32x32x16_bf16 v[0:15], v[64:67], v[136:139], v[0:15]
	v_exp_f32_e32 v124, v124
	v_exp_f32_e32 v125, v125
	v_exp_f32_e32 v126, v126
	v_exp_f32_e32 v127, v127
	s_waitcnt lgkmcnt(4)
	v_mfma_f32_32x32x16_bf16 v[48:63], v[64:67], v[128:131], v[48:63]
	v_exp_f32_e32 v96, v96
	v_exp_f32_e32 v97, v97
	v_exp_f32_e32 v98, v98
	v_exp_f32_e32 v99, v99
	v_exp_f32_e32 v100, v100
	s_waitcnt lgkmcnt(2)
	v_mfma_f32_32x32x16_bf16 v[32:47], v[64:67], v[88:91], v[32:47]
	v_exp_f32_e32 v101, v101
	v_exp_f32_e32 v102, v102
	v_exp_f32_e32 v103, v103
	v_exp_f32_e32 v104, v104
	v_exp_f32_e32 v105, v105
	s_waitcnt lgkmcnt(0)
	v_mfma_f32_32x32x16_bf16 v[16:31], v[64:67], v[72:75], v[16:31]
	v_exp_f32_e32 v106, v106
	v_exp_f32_e32 v107, v107
	v_exp_f32_e32 v108, v108
	v_exp_f32_e32 v109, v109
	v_exp_f32_e32 v110, v110
	v_exp_f32_e32 v111, v111
	v_cmp_gt_f32_e32 vcc, 1.0, v145
	s_cbranch_vccz .LBB0_238
	s_and_saveexec_b64 s[20:21], s[38:39]
	ds_write_b32 v182, v145 offset:128
	s_or_b64 exec, exec, s[20:21]
	s_waitcnt lgkmcnt(0)
	v_add_u32_e32 v76, s70, v162
	ds_read_b128 v[64:67], v76 offset:224
	ds_read_b128 v[68:71], v76 offset:192
	ds_read_b128 v[72:75], v76 offset:160
	ds_read_b128 v[76:79], v76 offset:128
	s_waitcnt lgkmcnt(3)
	v_pk_mul_f32 v[12:13], v[12:13], v[64:65]
	s_waitcnt lgkmcnt(2)
	v_pk_mul_f32 v[8:9], v[8:9], v[68:69]
	s_waitcnt lgkmcnt(1)
	v_pk_mul_f32 v[4:5], v[4:5], v[72:73]
	v_pk_mul_f32 v[14:15], v[14:15], v[66:67]
	v_pk_mul_f32 v[10:11], v[10:11], v[70:71]
	v_pk_mul_f32 v[6:7], v[6:7], v[74:75]
	s_waitcnt lgkmcnt(0)
	v_pk_mul_f32 v[2:3], v[2:3], v[78:79]
	v_pk_mul_f32 v[0:1], v[0:1], v[76:77]
	v_pk_mul_f32 v[60:61], v[60:61], v[64:65]
	v_pk_mul_f32 v[56:57], v[56:57], v[68:69]
	v_pk_mul_f32 v[52:53], v[52:53], v[72:73]
	v_pk_mul_f32 v[62:63], v[62:63], v[66:67]
	v_pk_mul_f32 v[58:59], v[58:59], v[70:71]
	v_pk_mul_f32 v[54:55], v[54:55], v[74:75]
	v_pk_mul_f32 v[50:51], v[50:51], v[78:79]
	v_pk_mul_f32 v[48:49], v[48:49], v[76:77]
	v_pk_mul_f32 v[44:45], v[44:45], v[64:65]
	v_pk_mul_f32 v[40:41], v[40:41], v[68:69]
	v_pk_mul_f32 v[36:37], v[36:37], v[72:73]
	v_pk_mul_f32 v[46:47], v[46:47], v[66:67]
	v_pk_mul_f32 v[42:43], v[42:43], v[70:71]
	v_pk_mul_f32 v[38:39], v[38:39], v[74:75]
	v_pk_mul_f32 v[34:35], v[34:35], v[78:79]
	v_pk_mul_f32 v[32:33], v[32:33], v[76:77]
	v_pk_mul_f32 v[28:29], v[28:29], v[64:65]
	v_pk_mul_f32 v[24:25], v[24:25], v[68:69]
	v_pk_mul_f32 v[20:21], v[20:21], v[72:73]
	v_pk_mul_f32 v[30:31], v[30:31], v[66:67]
	v_pk_mul_f32 v[26:27], v[26:27], v[70:71]
	v_pk_mul_f32 v[22:23], v[22:23], v[74:75]
	v_pk_mul_f32 v[18:19], v[18:19], v[78:79]
	v_pk_mul_f32 v[16:17], v[16:17], v[76:77]
.LBB0_238:
	v_add_f32_e32 v64, 0, v112
	v_add_f32_e32 v64, v113, v64
	v_add_f32_e32 v64, v114, v64
	v_add_f32_e32 v64, v115, v64
	v_add_f32_e32 v64, v116, v64
	v_add_f32_e32 v64, v117, v64
	v_add_f32_e32 v64, v118, v64
	v_add_f32_e32 v64, v119, v64
	v_add_f32_e32 v64, v120, v64
	v_add_f32_e32 v64, v121, v64
	v_add_f32_e32 v64, v122, v64
	v_add_f32_e32 v64, v123, v64
	v_add_f32_e32 v64, v124, v64
	v_add_f32_e32 v64, v125, v64
	v_add_f32_e32 v64, v126, v64
	v_add_f32_e32 v64, v127, v64
	v_add_f32_e32 v64, v96, v64
	v_add_f32_e32 v64, v97, v64
	v_add_f32_e32 v64, v98, v64
	v_add_f32_e32 v64, v99, v64
	v_add_f32_e32 v64, v100, v64
	v_add_f32_e32 v64, v101, v64
	v_add_f32_e32 v64, v102, v64
	v_add_f32_e32 v64, v103, v64
	v_add_f32_e32 v64, v104, v64
	v_add_f32_e32 v64, v105, v64
	v_add_f32_e32 v64, v106, v64
	v_add_f32_e32 v64, v107, v64
	v_add_f32_e32 v64, v108, v64
	v_add_f32_e32 v64, v109, v64
	v_add_f32_e32 v64, v110, v64
	s_waitcnt vmcnt(0) lgkmcnt(0)
	s_barrier
; #define SBAR() __builtin_amdgcn_sched_barrier(0)
; __device__ __forceinline__ int crow(int r, int hi) { return (r & 3) + 8 * (r >> 2) + 4 * hi; }
; __device__ __forceinline__ void pv_d0(f32x16* o, int vb, bf16x8 pa0, bf16x8 pa1, bf16x8 pa2, bf16x8 pa3) {
;     ...
;   KSTEP(0, pa0); KSTEP(1, pa1); KSTEP(2, pa2); KSTEP(3, pa3);
; __device__ __forceinline__ void attn_unit(const bf16* __restrict__ proj, bf16* __restrict__ cat, int b, int h, int qb, float lam, float oscale, const float* __restrict__ subln, const float* __restrict__ cw, char* lds) {
;     ...
;     { auto rr = __builtin_amdgcn_permlane32_swap(__float_as_uint(ps), __float_as_uint(ps), false, false); ps = __uint_as_float(rr[0]) + __uint_as_float(rr[1]); }
;     l_reg = l_reg * alB + ps; PK4(pB0, 0, pa0); PK4(pB0, 8, pa1); PK4(pB1, 0, pa2); PK4(pB1, 8, pa3); }
;   SBAR();
;   pv_d0(o, vb0 + ((sj == 0) ? 2 : sj - 1) * SHM_V, pa0, pa1, pa2, pa3);
;   if (hi == 0) li_l[r32] = l_reg; asm volatile("s_waitcnt lgkmcnt(0)" ::: "memory");
;   float rli[16];
; #pragma unroll
;   for (int r = 0; r < 16; ++r) rli[r] = __builtin_amdgcn_rcpf(li_l[crow(r, hi)]);
;   __syncthreads();
	s_lshl_b32 s20, s24, 2
	s_add_i32 s20, s20, s25
	s_mul_i32 s20, s20, 0x600
	s_add_i32 s20, s20, 0x18800
	v_mbcnt_lo_u32_b32 v73, -1, 0
	v_mbcnt_hi_u32_b32 v73, -1, v73
	v_lshl_add_u32 v73, v73, 2, s20
	ds_read_b32 v174, v73
	ds_read_b32 v175, v73 offset:256
	ds_read_b32 v176, v73 offset:512
	ds_read_b32 v177, v73 offset:768
	ds_read_b32 v178, v73 offset:1024
	ds_read_b32 v179, v73 offset:1280
	s_waitcnt lgkmcnt(0)
	v_add_f32_e32 v72, v111, v64
	v_fmac_f32_e32 v72, v144, v145
	v_mov_b32_e32 v73, v72
	s_nop 1
	v_permlane32_swap_b32_e32 v72, v73
	v_cvt_pk_bf16_f32 v74, v112, v113
	v_cvt_pk_bf16_f32 v75, v114, v115
	v_cvt_pk_bf16_f32 v76, v116, v117
	v_cvt_pk_bf16_f32 v77, v118, v119
	v_cvt_pk_bf16_f32 v78, v120, v121
	v_cvt_pk_bf16_f32 v79, v122, v123
	v_cvt_pk_bf16_f32 v80, v124, v125
	v_cvt_pk_bf16_f32 v81, v126, v127
	v_cvt_pk_bf16_f32 v68, v96, v97
	v_cvt_pk_bf16_f32 v69, v98, v99
	v_cvt_pk_bf16_f32 v70, v100, v101
	v_cvt_pk_bf16_f32 v71, v102, v103
	v_cvt_pk_bf16_f32 v64, v104, v105
	v_cvt_pk_bf16_f32 v65, v106, v107
	v_cvt_pk_bf16_f32 v66, v108, v109
	v_cvt_pk_bf16_f32 v67, v110, v111
	s_cmp_lg_u32 0, -1
	s_cselect_b32 s20, 0, 0
	v_add_u32_e32 v82, 0, v183
	v_add_u32_e32 v86, s20, v183
	ds_read_b64_tr_b16 v[82:83], v82 offset:49152
	ds_read_b64_tr_b16 v[84:85], v86 offset:51200
	s_waitcnt lgkmcnt(0)
	v_mfma_f32_32x32x16_bf16 v[0:15], v[74:77], v[82:85], v[0:15]
	ds_read_b64_tr_b16 v[84:85], v86 offset:51712
	ds_read_b64_tr_b16 v[82:83], v86 offset:49664
	s_waitcnt lgkmcnt(0)
	v_mfma_f32_32x32x16_bf16 v[48:63], v[74:77], v[82:85], v[48:63]
	ds_read_b64_tr_b16 v[82:83], v86 offset:50176
	ds_read_b64_tr_b16 v[84:85], v86 offset:52224
	s_waitcnt lgkmcnt(0)
	v_mfma_f32_32x32x16_bf16 v[32:47], v[74:77], v[82:85], v[32:47]
	ds_read_b64_tr_b16 v[82:83], v86 offset:50688
	ds_read_b64_tr_b16 v[84:85], v86 offset:52736
	s_waitcnt lgkmcnt(0)
	v_mfma_f32_32x32x16_bf16 v[16:31], v[74:77], v[82:85], v[16:31]
	ds_read_b64_tr_b16 v[74:75], v86 offset:53248
	ds_read_b64_tr_b16 v[76:77], v86 offset:55296
	s_waitcnt lgkmcnt(0)
	v_mfma_f32_32x32x16_bf16 v[0:15], v[78:81], v[74:77], v[0:15]
	ds_read_b64_tr_b16 v[76:77], v86 offset:55808
	ds_read_b64_tr_b16 v[74:75], v86 offset:53760
	s_waitcnt lgkmcnt(0)
	v_mfma_f32_32x32x16_bf16 v[48:63], v[78:81], v[74:77], v[48:63]
	ds_read_b64_tr_b16 v[74:75], v86 offset:54272
	ds_read_b64_tr_b16 v[76:77], v86 offset:56320
	s_waitcnt lgkmcnt(0)
	v_mfma_f32_32x32x16_bf16 v[32:47], v[78:81], v[74:77], v[32:47]
	ds_read_b64_tr_b16 v[74:75], v86 offset:54784
	ds_read_b64_tr_b16 v[76:77], v86 offset:56832
	s_waitcnt lgkmcnt(0)
	v_mfma_f32_32x32x16_bf16 v[16:31], v[78:81], v[74:77], v[16:31]
	ds_read_b64_tr_b16 v[74:75], v86 offset:57344
	ds_read_b64_tr_b16 v[76:77], v86 offset:59392
	s_waitcnt lgkmcnt(0)
	v_mfma_f32_32x32x16_bf16 v[0:15], v[68:71], v[74:77], v[0:15]
	ds_read_b64_tr_b16 v[76:77], v86 offset:59904
	ds_read_b64_tr_b16 v[74:75], v86 offset:57856
	s_waitcnt lgkmcnt(0)
	v_mfma_f32_32x32x16_bf16 v[48:63], v[68:71], v[74:77], v[48:63]
	ds_read_b64_tr_b16 v[74:75], v86 offset:58368
	ds_read_b64_tr_b16 v[76:77], v86 offset:60416
	s_waitcnt lgkmcnt(0)
	v_mfma_f32_32x32x16_bf16 v[32:47], v[68:71], v[74:77], v[32:47]
	ds_read_b64_tr_b16 v[74:75], v86 offset:58880
	ds_read_b64_tr_b16 v[76:77], v86 offset:60928
	s_waitcnt lgkmcnt(0)
	v_mfma_f32_32x32x16_bf16 v[16:31], v[68:71], v[74:77], v[16:31]
	ds_read_b64_tr_b16 v[68:69], v86 offset:61440
	ds_read_b64_tr_b16 v[70:71], v86 offset:63488
	s_waitcnt lgkmcnt(0)
	v_mfma_f32_32x32x16_bf16 v[0:15], v[64:67], v[68:71], v[0:15]
	ds_read_b64_tr_b16 v[70:71], v86 offset:64000
	ds_read_b64_tr_b16 v[68:69], v86 offset:61952
	s_waitcnt lgkmcnt(0)
	v_mfma_f32_32x32x16_bf16 v[48:63], v[64:67], v[68:71], v[48:63]
	ds_read_b64_tr_b16 v[68:69], v86 offset:62464
	ds_read_b64_tr_b16 v[70:71], v86 offset:64512
	s_waitcnt lgkmcnt(0)
	v_mfma_f32_32x32x16_bf16 v[32:47], v[64:67], v[68:71], v[32:47]
	ds_read_b64_tr_b16 v[68:69], v86 offset:62976
	ds_read_b64_tr_b16 v[70:71], v86 offset:65024
	s_waitcnt lgkmcnt(0)
	v_mfma_f32_32x32x16_bf16 v[16:31], v[64:67], v[68:71], v[16:31]
	s_and_saveexec_b64 s[20:21], s[38:39]
	v_add_f32_e32 v64, v72, v73
	ds_write_b32 v182, v64
	s_or_b64 exec, exec, s[20:21]
	s_waitcnt lgkmcnt(0)
	v_add_u32_e32 v72, s70, v162
	ds_read_b128 v[64:67], v72
	ds_read_b128 v[68:71], v72 offset:32
	s_lshl_b32 s20, s25, 14
	s_add_i32 s20, s20, 0
	s_cmp_lg_u32 s24, 1
	s_waitcnt lgkmcnt(1)
	v_rcp_f32_e32 v150, v64
	v_rcp_f32_e32 v149, v65
	v_rcp_f32_e32 v148, v66
	v_rcp_f32_e32 v147, v67
	s_waitcnt lgkmcnt(0)
	v_rcp_f32_e32 v146, v68
	ds_read_b128 v[64:67], v72 offset:64
	v_rcp_f32_e32 v145, v69
	v_rcp_f32_e32 v144, v70
	v_rcp_f32_e32 v143, v71
	ds_read_b128 v[68:71], v72 offset:96
	s_waitcnt lgkmcnt(1)
	v_rcp_f32_e32 v142, v64
	v_rcp_f32_e32 v141, v65
	v_rcp_f32_e32 v140, v66
	v_rcp_f32_e32 v139, v67
	s_waitcnt lgkmcnt(0)
	v_rcp_f32_e32 v138, v68
	v_rcp_f32_e32 v137, v69
	v_rcp_f32_e32 v135, v70
	v_rcp_f32_e32 v134, v71
	v_lshl_add_u32 v136, v177, 2, s20
	s_barrier
	s_cbranch_scc1 .LBB0_242
; __device__ __forceinline__ void attn_unit(const bf16* __restrict__ proj, bf16* __restrict__ cat, int b, int h, int qb, float lam, float oscale, const float* __restrict__ subln, const float* __restrict__ cw, char* lds) {
;     ...
;   float* X = (float*)(lds + rg * 16384);
;   if (mp == 1) {
; #pragma unroll
;     for (int d0 = 0; d0 < 4; ++d0)
; #pragma unroll
;       for (int r = 0; r < 16; ++r) X[(d0 * 16 + r) * 64 + lane] = o[d0][r] * rli[r] * lam;
;   }
	v_mul_f32_e32 v64, v0, v150
	v_mul_f32_e32 v65, v1, v149
	v_mul_f32_e32 v64, v176, v64
	v_mul_f32_e32 v65, v176, v65
	ds_write2st64_b32 v136, v64, v65 offset1:1
	v_mul_f32_e32 v64, v2, v148
	v_mul_f32_e32 v65, v3, v147
	v_mul_f32_e32 v64, v176, v64
	v_mul_f32_e32 v65, v176, v65
	ds_write2st64_b32 v136, v64, v65 offset0:2 offset1:3
	v_mul_f32_e32 v64, v4, v146
	v_mul_f32_e32 v65, v5, v145
	v_mul_f32_e32 v64, v176, v64
	v_mul_f32_e32 v65, v176, v65
	ds_write2st64_b32 v136, v64, v65 offset0:4 offset1:5
	v_mul_f32_e32 v64, v6, v144
	v_mul_f32_e32 v65, v7, v143
	v_mul_f32_e32 v64, v176, v64
	v_mul_f32_e32 v65, v176, v65
	ds_write2st64_b32 v136, v64, v65 offset0:6 offset1:7
	v_mul_f32_e32 v64, v8, v142
	v_mul_f32_e32 v65, v9, v141
	v_mul_f32_e32 v64, v176, v64
	v_mul_f32_e32 v65, v176, v65
	ds_write2st64_b32 v136, v64, v65 offset0:8 offset1:9
	v_mul_f32_e32 v64, v10, v140
	v_mul_f32_e32 v65, v11, v139
	v_mul_f32_e32 v64, v176, v64
	v_mul_f32_e32 v65, v176, v65
	ds_write2st64_b32 v136, v64, v65 offset0:10 offset1:11
	v_mul_f32_e32 v64, v12, v138
	v_mul_f32_e32 v65, v13, v137
	v_mul_f32_e32 v64, v176, v64
	v_mul_f32_e32 v65, v176, v65
	ds_write2st64_b32 v136, v64, v65 offset0:12 offset1:13
	v_mul_f32_e32 v64, v14, v135
	v_mul_f32_e32 v65, v15, v134
	v_mul_f32_e32 v64, v176, v64
	v_mul_f32_e32 v65, v176, v65
	ds_write2st64_b32 v136, v64, v65 offset0:14 offset1:15
	v_mul_f32_e32 v64, v48, v150
	v_mul_f32_e32 v65, v49, v149
	v_mul_f32_e32 v64, v176, v64
	v_mul_f32_e32 v65, v176, v65
	ds_write2st64_b32 v136, v64, v65 offset0:16 offset1:17
	v_mul_f32_e32 v64, v50, v148
	v_mul_f32_e32 v65, v51, v147
	v_mul_f32_e32 v64, v176, v64
	v_mul_f32_e32 v65, v176, v65
	ds_write2st64_b32 v136, v64, v65 offset0:18 offset1:19
	v_mul_f32_e32 v64, v52, v146
	v_mul_f32_e32 v65, v53, v145
	v_mul_f32_e32 v64, v176, v64
	v_mul_f32_e32 v65, v176, v65
	ds_write2st64_b32 v136, v64, v65 offset0:20 offset1:21
	v_mul_f32_e32 v64, v54, v144
	v_mul_f32_e32 v65, v55, v143
	v_mul_f32_e32 v64, v176, v64
	v_mul_f32_e32 v65, v176, v65
	ds_write2st64_b32 v136, v64, v65 offset0:22 offset1:23
	v_mul_f32_e32 v64, v56, v142
	v_mul_f32_e32 v65, v57, v141
	v_mul_f32_e32 v64, v176, v64
	v_mul_f32_e32 v65, v176, v65
	ds_write2st64_b32 v136, v64, v65 offset0:24 offset1:25
	v_mul_f32_e32 v64, v58, v140
	v_mul_f32_e32 v65, v59, v139
	v_mul_f32_e32 v64, v176, v64
	v_mul_f32_e32 v65, v176, v65
	ds_write2st64_b32 v136, v64, v65 offset0:26 offset1:27
	v_mul_f32_e32 v64, v60, v138
	v_mul_f32_e32 v65, v61, v137
	v_mul_f32_e32 v64, v176, v64
	v_mul_f32_e32 v65, v176, v65
	ds_write2st64_b32 v136, v64, v65 offset0:28 offset1:29
	v_mul_f32_e32 v64, v62, v135
	v_mul_f32_e32 v65, v63, v134
	v_mul_f32_e32 v64, v176, v64
	v_mul_f32_e32 v65, v176, v65
	ds_write2st64_b32 v136, v64, v65 offset0:30 offset1:31
	v_mul_f32_e32 v64, v32, v150
	v_mul_f32_e32 v65, v33, v149
	v_mul_f32_e32 v64, v176, v64
	v_mul_f32_e32 v65, v176, v65
	ds_write2st64_b32 v136, v64, v65 offset0:32 offset1:33
	v_mul_f32_e32 v64, v34, v148
	v_mul_f32_e32 v65, v35, v147
	v_mul_f32_e32 v64, v176, v64
	v_mul_f32_e32 v65, v176, v65
	ds_write2st64_b32 v136, v64, v65 offset0:34 offset1:35
	v_mul_f32_e32 v64, v36, v146
	v_mul_f32_e32 v65, v37, v145
	v_mul_f32_e32 v64, v176, v64
	v_mul_f32_e32 v65, v176, v65
	ds_write2st64_b32 v136, v64, v65 offset0:36 offset1:37
	v_mul_f32_e32 v64, v38, v144
	v_mul_f32_e32 v65, v39, v143
	v_mul_f32_e32 v64, v176, v64
	v_mul_f32_e32 v65, v176, v65
	ds_write2st64_b32 v136, v64, v65 offset0:38 offset1:39
	v_mul_f32_e32 v64, v40, v142
	v_mul_f32_e32 v65, v41, v141
	v_mul_f32_e32 v64, v176, v64
	v_mul_f32_e32 v65, v176, v65
	ds_write2st64_b32 v136, v64, v65 offset0:40 offset1:41
	v_mul_f32_e32 v64, v42, v140
	v_mul_f32_e32 v65, v43, v139
	v_mul_f32_e32 v64, v176, v64
	v_mul_f32_e32 v65, v176, v65
	ds_write2st64_b32 v136, v64, v65 offset0:42 offset1:43
	v_mul_f32_e32 v64, v44, v138
	v_mul_f32_e32 v65, v45, v137
	v_mul_f32_e32 v64, v176, v64
	v_mul_f32_e32 v65, v176, v65
	ds_write2st64_b32 v136, v64, v65 offset0:44 offset1:45
	v_mul_f32_e32 v64, v46, v135
	v_mul_f32_e32 v65, v47, v134
	v_mul_f32_e32 v64, v176, v64
	v_mul_f32_e32 v65, v176, v65
	ds_write2st64_b32 v136, v64, v65 offset0:46 offset1:47
	v_mul_f32_e32 v64, v16, v150
	v_mul_f32_e32 v65, v17, v149
	v_mul_f32_e32 v64, v176, v64
	v_mul_f32_e32 v65, v176, v65
	ds_write2st64_b32 v136, v64, v65 offset0:48 offset1:49
	v_mul_f32_e32 v64, v18, v148
	v_mul_f32_e32 v65, v19, v147
	v_mul_f32_e32 v64, v176, v64
	v_mul_f32_e32 v65, v176, v65
	ds_write2st64_b32 v136, v64, v65 offset0:50 offset1:51
	v_mul_f32_e32 v64, v20, v146
	v_mul_f32_e32 v65, v21, v145
	v_mul_f32_e32 v64, v176, v64
	v_mul_f32_e32 v65, v176, v65
	ds_write2st64_b32 v136, v64, v65 offset0:52 offset1:53
	v_mul_f32_e32 v64, v22, v144
	v_mul_f32_e32 v65, v23, v143
	v_mul_f32_e32 v64, v176, v64
	v_mul_f32_e32 v65, v176, v65
	ds_write2st64_b32 v136, v64, v65 offset0:54 offset1:55
	v_mul_f32_e32 v64, v24, v142
	v_mul_f32_e32 v65, v25, v141
	v_mul_f32_e32 v64, v176, v64
	v_mul_f32_e32 v65, v176, v65
	ds_write2st64_b32 v136, v64, v65 offset0:56 offset1:57
	v_mul_f32_e32 v64, v26, v140
	v_mul_f32_e32 v65, v27, v139
	v_mul_f32_e32 v64, v176, v64
	v_mul_f32_e32 v65, v176, v65
	ds_write2st64_b32 v136, v64, v65 offset0:58 offset1:59
	v_mul_f32_e32 v64, v28, v138
	v_mul_f32_e32 v65, v29, v137
	v_mul_f32_e32 v64, v176, v64
	v_mul_f32_e32 v65, v176, v65
	ds_write2st64_b32 v136, v64, v65 offset0:60 offset1:61
	v_mul_f32_e32 v64, v30, v135
	v_mul_f32_e32 v65, v31, v134
	v_mul_f32_e32 v64, v176, v64
	v_mul_f32_e32 v65, v176, v65
	ds_write2st64_b32 v136, v64, v65 offset0:62 offset1:63

.Latt_rare_1:
	v_mov_b32_e32 v196, v197
	s_nop 1
	v_permlane32_swap_b32_e32 v197, v196
	v_max_f32_e32 v196, v196, v196
	v_max_f32_e32 v197, v197, v197
	v_max_f32_e32 v196, v197, v196
	v_max_f32_e32 v196, 0, v196
	v_add_f32_e32 v220, v218, v196
	v_sub_f32_e32 v196, v220, v218
	v_exp_f32_e64 v218, -v196
	v_xor_b32_e32 v164, 0x80000000, v220
	v_xor_b32_e32 v165, 0x80000000, v220
	v_xor_b32_e32 v166, 0x80000000, v220
	v_xor_b32_e32 v167, 0x80000000, v220
	v_xor_b32_e32 v168, 0x80000000, v220
	v_xor_b32_e32 v169, 0x80000000, v220
	v_xor_b32_e32 v170, 0x80000000, v220
	v_xor_b32_e32 v171, 0x80000000, v220
	v_xor_b32_e32 v172, 0x80000000, v220
	v_xor_b32_e32 v173, 0x80000000, v220
	v_xor_b32_e32 v174, 0x80000000, v220
	v_xor_b32_e32 v175, 0x80000000, v220
	v_xor_b32_e32 v176, 0x80000000, v220
	v_xor_b32_e32 v177, 0x80000000, v220
	v_xor_b32_e32 v178, 0x80000000, v220
	v_xor_b32_e32 v179, 0x80000000, v220
	v_sub_f32_e32 v96, v96, v196
	v_sub_f32_e32 v97, v97, v196
	v_sub_f32_e32 v98, v98, v196
	v_sub_f32_e32 v99, v99, v196
	v_sub_f32_e32 v100, v100, v196
	v_sub_f32_e32 v101, v101, v196
	v_sub_f32_e32 v102, v102, v196
	v_sub_f32_e32 v103, v103, v196
	v_sub_f32_e32 v104, v104, v196
	v_sub_f32_e32 v105, v105, v196
	v_sub_f32_e32 v106, v106, v196
	v_sub_f32_e32 v107, v107, v196
	v_sub_f32_e32 v108, v108, v196
	v_sub_f32_e32 v109, v109, v196
	v_sub_f32_e32 v110, v110, v196
	v_sub_f32_e32 v111, v111, v196
	v_sub_f32_e32 v112, v112, v196
	v_sub_f32_e32 v113, v113, v196
	v_sub_f32_e32 v114, v114, v196
	v_sub_f32_e32 v115, v115, v196
	v_sub_f32_e32 v116, v116, v196
	v_sub_f32_e32 v117, v117, v196
	v_sub_f32_e32 v118, v118, v196
	v_sub_f32_e32 v119, v119, v196
	v_sub_f32_e32 v120, v120, v196
	v_sub_f32_e32 v121, v121, v196
	v_sub_f32_e32 v122, v122, v196
	v_sub_f32_e32 v123, v123, v196
	v_sub_f32_e32 v124, v124, v196
	v_sub_f32_e32 v125, v125, v196
	v_sub_f32_e32 v126, v126, v196
	v_sub_f32_e32 v127, v127, v196
	s_branch .Latt_back_1
.Latt_rare_2:
	v_mov_b32_e32 v196, v197
	s_nop 1
	v_permlane32_swap_b32_e32 v197, v196
	v_max_f32_e32 v196, v196, v196
	v_max_f32_e32 v197, v197, v197
	v_max_f32_e32 v196, v197, v196
	v_max_f32_e32 v196, 0, v196
	v_add_f32_e32 v218, v220, v196
	v_sub_f32_e32 v196, v218, v220
	v_exp_f32_e64 v220, -v196
	v_xor_b32_e32 v164, 0x80000000, v218
	v_xor_b32_e32 v165, 0x80000000, v218
	v_xor_b32_e32 v166, 0x80000000, v218
	v_xor_b32_e32 v167, 0x80000000, v218
	v_xor_b32_e32 v168, 0x80000000, v218
	v_xor_b32_e32 v169, 0x80000000, v218
	v_xor_b32_e32 v170, 0x80000000, v218
	v_xor_b32_e32 v171, 0x80000000, v218
	v_xor_b32_e32 v172, 0x80000000, v218
	v_xor_b32_e32 v173, 0x80000000, v218
	v_xor_b32_e32 v174, 0x80000000, v218
	v_xor_b32_e32 v175, 0x80000000, v218
	v_xor_b32_e32 v176, 0x80000000, v218
	v_xor_b32_e32 v177, 0x80000000, v218
	v_xor_b32_e32 v178, 0x80000000, v218
	v_xor_b32_e32 v179, 0x80000000, v218
	v_sub_f32_e32 v64, v64, v196
	v_sub_f32_e32 v65, v65, v196
	v_sub_f32_e32 v66, v66, v196
	v_sub_f32_e32 v67, v67, v196
	v_sub_f32_e32 v68, v68, v196
	v_sub_f32_e32 v69, v69, v196
	v_sub_f32_e32 v70, v70, v196
	v_sub_f32_e32 v71, v71, v196
	v_sub_f32_e32 v72, v72, v196
	v_sub_f32_e32 v73, v73, v196
	v_sub_f32_e32 v74, v74, v196
	v_sub_f32_e32 v75, v75, v196
	v_sub_f32_e32 v76, v76, v196
	v_sub_f32_e32 v77, v77, v196
	v_sub_f32_e32 v78, v78, v196
	v_sub_f32_e32 v79, v79, v196
	v_sub_f32_e32 v80, v80, v196
	v_sub_f32_e32 v81, v81, v196
	v_sub_f32_e32 v82, v82, v196
	v_sub_f32_e32 v83, v83, v196
	v_sub_f32_e32 v84, v84, v196
	v_sub_f32_e32 v85, v85, v196
	v_sub_f32_e32 v86, v86, v196
	v_sub_f32_e32 v87, v87, v196
	v_sub_f32_e32 v88, v88, v196
	v_sub_f32_e32 v89, v89, v196
	v_sub_f32_e32 v90, v90, v196
	v_sub_f32_e32 v91, v91, v196
	v_sub_f32_e32 v92, v92, v196
	v_sub_f32_e32 v93, v93, v196
	v_sub_f32_e32 v94, v94, v196
	v_sub_f32_e32 v95, v95, v196
	s_branch .Latt_back_2
.Latt_rare_3:
	v_mov_b32_e32 v145, v150
	s_nop 1
	v_permlane32_swap_b32_e32 v150, v145
	v_max_f32_e32 v145, v145, v145
	v_max_f32_e32 v150, v150, v150
	v_max_f32_e32 v145, v150, v145
	v_max_f32_e32 v145, 0, v145
	v_add_f32_e32 v150, v218, v145
	v_sub_f32_e32 v150, v150, v218
	v_exp_f32_e64 v145, -v150
	v_sub_f32_e32 v96, v96, v150
	v_sub_f32_e32 v97, v97, v150
	v_sub_f32_e32 v98, v98, v150
	v_sub_f32_e32 v99, v99, v150
	v_sub_f32_e32 v100, v100, v150
	v_sub_f32_e32 v101, v101, v150
	v_sub_f32_e32 v102, v102, v150
	v_sub_f32_e32 v103, v103, v150
	v_sub_f32_e32 v104, v104, v150
	v_sub_f32_e32 v105, v105, v150
	v_sub_f32_e32 v106, v106, v150
	v_sub_f32_e32 v107, v107, v150
	v_sub_f32_e32 v108, v108, v150
	v_sub_f32_e32 v109, v109, v150
	v_sub_f32_e32 v110, v110, v150
	v_sub_f32_e32 v111, v111, v150
	v_sub_f32_e32 v112, v112, v150
	v_sub_f32_e32 v113, v113, v150
	v_sub_f32_e32 v114, v114, v150
	v_sub_f32_e32 v115, v115, v150
	v_sub_f32_e32 v116, v116, v150
	v_sub_f32_e32 v117, v117, v150
	v_sub_f32_e32 v118, v118, v150
	v_sub_f32_e32 v119, v119, v150
	v_sub_f32_e32 v120, v120, v150
	v_sub_f32_e32 v121, v121, v150
	v_sub_f32_e32 v122, v122, v150
	v_sub_f32_e32 v123, v123, v150
	v_sub_f32_e32 v124, v124, v150
	v_sub_f32_e32 v125, v125, v150
	v_sub_f32_e32 v126, v126, v150
	v_sub_f32_e32 v127, v127, v150
	s_branch .Latt_back_3

;     __host__ __device__ bool next(int i, Unit& u) const {
;         const long L = (long)i * G + c; if (L >= nwg) return false;
;         int wgid = (int)L; { const int q = nwg / NXCD, r = nwg % NXCD, xcd = wgid % NXCD, off = wgid / NXCD; wgid = (xcd < r ? xcd * (q + 1) : r * (q + 1) + (xcd - r) * q) + off; }
;         const int nig = WGM * nN, gid = wgid / nig, fm = gid * WGM, gsz = (nM - fm) < WGM ? (nM - fm) : WGM;
;         u.pm = fm + ((wgid % nig) % gsz); u.pn = (wgid % nig) / gsz; return true;
;     }
.LBB0_309:
	s_add_i32 s74, s74, 1
	s_mul_i32 s20, s74, s49
	s_mul_hi_u32 s21, s74, s98
	s_add_i32 s21, s21, s20
	s_mul_i32 s20, s74, s98
	s_add_u32 s20, s20, s2
	s_addc_u32 s21, s21, s48
	v_mov_b64_e32 v[168:169], 0x1ff
	v_mov_b64_e32 v[166:167], 0x200
	v_cmp_gt_i64_e32 vcc, s[20:21], v[168:169]
	v_cmp_lt_i64_e64 s[42:43], s[20:21], v[166:167]
	s_cbranch_vccnz .LBB0_315
	s_ashr_i32 s21, s20, 31
	s_lshr_b32 s21, s21, 29
	s_add_i32 s76, s20, s21
	s_and_b32 s21, s76, -8
	s_sub_i32 s77, s20, s21
	s_cmp_gt_i32 s77, -1
	s_mov_b64 s[20:21], -1
	s_cbranch_scc0 .LBB0_312
	s_lshl_b32 s78, s77, 6
	s_mov_b64 s[20:21], 0

;     __host__ __device__ bool next(int i, Unit& u) const {
;         const long L = (long)i * G + c; if (L >= nwg) return false;
;         int wgid = (int)L; { const int q = nwg / NXCD, r = nwg % NXCD, xcd = wgid % NXCD, off = wgid / NXCD; wgid = (xcd < r ? xcd * (q + 1) : r * (q + 1) + (xcd - r) * q) + off; }
;         const int nig = WGM * nN, gid = wgid / nig, fm = gid * WGM, gsz = (nM - fm) < WGM ? (nM - fm) : WGM;
;         u.pm = fm + ((wgid % nig) % gsz); u.pn = (wgid % nig) / gsz; return true;
;     }
.LBB0_365:
	s_add_i32 s75, s75, 1
	s_mul_i32 s42, s75, s49
	s_mul_hi_u32 s43, s75, s98
	s_add_i32 s43, s43, s42
	s_mul_i32 s42, s75, s98
	s_add_u32 s88, s42, s2
	s_addc_u32 s89, s43, s48
	v_mov_b64_e32 v[172:173], 0xaff
	v_mov_b64_e32 v[170:171], 0xb00
	v_cmp_gt_i64_e32 vcc, s[88:89], v[172:173]
	v_cmp_lt_i64_e64 s[42:43], s[88:89], v[170:171]
	s_cbranch_vccnz .LBB0_367
	s_ashr_i32 s46, s88, 31
	s_lshr_b32 s46, s46, 29
	s_add_i32 s46, s88, s46
	s_ashr_i32 s47, s46, 3
	s_and_b32 s46, s46, -8
	s_sub_i32 s46, s88, s46
	s_cmp_lt_i32 s46, 0
	s_cselect_b32 s78, s17, 0x160
	s_mul_i32 s46, s46, s78
	s_add_i32 s46, s46, s47
	s_mul_hi_i32 s47, s46, 0x2e8ba2e9
	s_lshr_b32 s78, s47, 31
	s_ashr_i32 s47, s47, 6
	s_add_i32 s47, s47, s78
	s_lshl_b32 s78, s47, 3
	s_sub_i32 s79, 64, s78
	s_min_i32 s79, s79, 8
	s_abs_i32 s81, s79
	v_cvt_f32_u32_e32 v0, s81
	s_sub_i32 s85, 0, s81
	s_mulk_i32 s47, 0x160
	s_sub_i32 s46, s46, s47
	v_rcp_iflag_f32_e32 v0, v0
	s_abs_i32 s47, s46
	s_xor_b32 s84, s46, s79
	s_ashr_i32 s84, s84, 31
	v_mul_f32_e32 v0, 0x4f7ffffe, v0
	v_cvt_u32_f32_e32 v0, v0
	s_nop 0
	v_readfirstlane_b32 s86, v0
	s_mul_i32 s85, s85, s86
	s_mul_hi_u32 s85, s86, s85
	s_add_i32 s86, s86, s85
	s_mul_hi_u32 s85, s47, s86
	s_mul_i32 s86, s85, s81
	s_sub_i32 s47, s47, s86
	s_add_i32 s87, s85, 1
	s_sub_i32 s86, s47, s81
	s_cmp_ge_u32 s47, s81
	s_cselect_b32 s85, s87, s85
	s_cselect_b32 s47, s86, s47
	s_add_i32 s86, s85, 1
	s_cmp_ge_u32 s47, s81
	s_cselect_b32 s47, s86, s85
	s_xor_b32 s47, s47, s84
	s_sub_i32 s84, s47, s84
	s_mul_i32 s47, s84, s79
	s_sub_i32 s46, s46, s47
	s_add_i32 s86, s78, s46

;     __host__ __device__ bool next(int i, Unit& u) const {
;         const long L = (long)i * G + c; if (L >= nwg) return false;
;         int wgid = (int)L; { const int q = nwg / NXCD, r = nwg % NXCD, xcd = wgid % NXCD, off = wgid / NXCD; wgid = (xcd < r ? xcd * (q + 1) : r * (q + 1) + (xcd - r) * q) + off; }
;         const int nig = WGM * nN, gid = wgid / nig, fm = gid * WGM, gsz = (nM - fm) < WGM ? (nM - fm) : WGM;
;         u.pm = fm + ((wgid % nig) % gsz); u.pn = (wgid % nig) / gsz; return true;
;     }
.LBB0_395:
	s_add_i32 s74, s74, 1
	s_mul_i32 s28, s74, s49
	s_mul_hi_u32 s29, s74, s98
	s_add_i32 s29, s29, s28
	s_mul_i32 s28, s74, s98
	s_add_u32 s28, s28, s2
	s_addc_u32 s29, s29, s48
	v_mov_b64_e32 v[168:169], 0x1ff
	v_mov_b64_e32 v[166:167], 0x200
	v_cmp_gt_i64_e32 vcc, s[28:29], v[168:169]
	v_cmp_lt_i64_e64 s[44:45], s[28:29], v[166:167]
	s_cbranch_vccnz .LBB0_401
	s_ashr_i32 s29, s28, 31
	s_lshr_b32 s29, s29, 29
	s_add_i32 s42, s28, s29
	s_and_b32 s29, s42, -8
	s_sub_i32 s43, s28, s29
	s_cmp_gt_i32 s43, -1
	s_mov_b64 s[28:29], -1
	s_cbranch_scc0 .LBB0_398
	s_lshl_b32 s75, s43, 6
	s_mov_b64 s[28:29], 0
